# lever 8 MFMA/LDS interleave: software-pipelined LDS fragment reads in the HGRN2 scan phase (phase 14), on top of the add64 variant
# baseline (speedup 1.0000x reference)
.LBB0_1461:
	s_or_b64 exec, exec, s[58:59]
	v_sub_f32_e32 v32, v66, v33
	v_exp_f32_e32 v66, v32
	v_sub_f32_e32 v32, v75, v35
	v_exp_f32_e32 v160, v32
	v_mov_b32_e32 v32, v38
	v_mov_b32_e32 v33, v36
	v_pk_mul_f32 v[32:33], v[66:67], v[32:33] op_sel_hi:[0,1]
	v_mov_b32_e32 v36, v39
	v_cvt_pk_bf16_f32 v39, v32, v33
	v_mov_b32_e32 v32, v42
	v_mov_b32_e32 v33, v40
	v_pk_mul_f32 v[32:33], v[66:67], v[32:33] op_sel_hi:[0,1]
	v_mov_b32_e32 v40, v43
	v_cvt_pk_bf16_f32 v38, v32, v33
	v_mov_b32_e32 v32, v46
	v_mov_b32_e32 v33, v44
	v_mov_b32_e32 v44, v47
	v_pk_mul_f32 v[34:35], v[160:161], v[36:37] op_sel_hi:[0,1]
	v_pk_mul_f32 v[36:37], v[160:161], v[40:41] op_sel_hi:[0,1]
	v_pk_mul_f32 v[32:33], v[66:67], v[32:33] op_sel_hi:[0,1]
	v_pk_mul_f32 v[40:41], v[160:161], v[44:45] op_sel_hi:[0,1]
	v_cvt_pk_bf16_f32 v35, v34, v35
	v_cvt_pk_bf16_f32 v34, v36, v37
	v_cvt_pk_bf16_f32 v37, v32, v33
	v_cvt_pk_bf16_f32 v33, v40, v41
	v_mov_b32_e32 v40, v50
	v_mov_b32_e32 v41, v48
	v_pk_mul_f32 v[40:41], v[66:67], v[40:41] op_sel_hi:[0,1]
	v_cvt_pk_bf16_f32 v36, v40, v41
	v_mov_b32_e32 v40, v56
	v_mov_b32_e32 v41, v52
	v_pk_mul_f32 v[40:41], v[66:67], v[40:41] op_sel_hi:[0,1]
	v_mov_b32_e32 v48, v51
	v_cvt_pk_bf16_f32 v51, v40, v41
	v_mov_b32_e32 v40, v96
	v_mov_b32_e32 v41, v60
	v_pk_mul_f32 v[42:43], v[160:161], v[48:49] op_sel_hi:[0,1]
	v_mov_b32_e32 v52, v57
	v_pk_mul_f32 v[40:41], v[66:67], v[40:41] op_sel_hi:[0,1]
	v_mov_b32_e32 v60, v97
	v_cvt_pk_bf16_f32 v32, v42, v43
	v_pk_mul_f32 v[42:43], v[160:161], v[52:53] op_sel_hi:[0,1]
	v_pk_mul_f32 v[44:45], v[160:161], v[60:61] op_sel_hi:[0,1]
	v_cvt_pk_bf16_f32 v50, v40, v41
	v_mov_b32_e32 v40, v62
	v_mov_b32_e32 v41, v98
	v_mov_b32_e32 v98, v63
	v_cvt_pk_bf16_f32 v43, v42, v43
	v_cvt_pk_bf16_f32 v42, v44, v45
	v_pk_mul_f32 v[40:41], v[66:67], v[40:41] op_sel_hi:[0,1]
	v_pk_mul_f32 v[44:45], v[160:161], v[98:99] op_sel_hi:[0,1]
	v_cvt_pk_bf16_f32 v49, v40, v41
	v_cvt_pk_bf16_f32 v41, v44, v45
	v_mov_b32_e32 v44, v54
	v_mov_b32_e32 v45, v58
	v_mov_b32_e32 v58, v55
	v_pk_mul_f32 v[44:45], v[66:67], v[44:45] op_sel_hi:[0,1]
	v_pk_mul_f32 v[46:47], v[160:161], v[58:59] op_sel_hi:[0,1]
	v_cvt_pk_bf16_f32 v48, v44, v45
	v_cvt_pk_bf16_f32 v40, v46, v47
	s_waitcnt lgkmcnt(0)
	s_barrier
	s_waitcnt lgkmcnt(0)
	ds_read_b128 v[216:219], v108
	v_add_u32_e32 v52, v109, v111
	v_add_u32_e32 v92, -1, v92
	s_add_i32 s73, s73, 1
	s_waitcnt lgkmcnt(0)
	v_pk_mul_f32 v[44:45], v[16:17], v[216:217]
	v_pk_mul_f32 v[46:47], v[18:19], v[218:219]
	v_cvt_pk_bf16_f32 v44, v44, v45
	v_cvt_pk_bf16_f32 v45, v46, v47
	ds_write_b64 v52, v[44:45] offset:45056
	ds_read_b128 v[220:223], v108 offset:64
	s_waitcnt lgkmcnt(0)
	v_pk_mul_f32 v[44:45], v[0:1], v[220:221]
	v_pk_mul_f32 v[46:47], v[2:3], v[222:223]
	v_cvt_pk_bf16_f32 v44, v44, v45
	v_cvt_pk_bf16_f32 v45, v46, v47
	ds_write_b64 v116, v[44:45] offset:45056
	ds_read_b128 v[224:227], v108 offset:128
	s_waitcnt lgkmcnt(0)
	v_pk_mul_f32 v[44:45], v[8:9], v[224:225]
	v_pk_mul_f32 v[46:47], v[10:11], v[226:227]
	v_cvt_pk_bf16_f32 v44, v44, v45
	v_cvt_pk_bf16_f32 v45, v46, v47
	ds_write_b64 v117, v[44:45] offset:45056
	ds_read_b128 v[228:231], v108 offset:192
	s_waitcnt lgkmcnt(0)
	v_pk_mul_f32 v[44:45], v[4:5], v[228:229]
	v_pk_mul_f32 v[46:47], v[6:7], v[230:231]
	v_cvt_pk_bf16_f32 v44, v44, v45
	v_cvt_pk_bf16_f32 v45, v46, v47
	ds_write_b64 v118, v[44:45] offset:45056
	ds_read_b128 v[232:235], v108 offset:256
	s_waitcnt lgkmcnt(0)
	v_pk_mul_f32 v[44:45], v[20:21], v[232:233]
	v_pk_mul_f32 v[46:47], v[22:23], v[234:235]
	v_cvt_pk_bf16_f32 v44, v44, v45
	v_cvt_pk_bf16_f32 v45, v46, v47
	ds_write_b64 v52, v[44:45] offset:45184
	ds_read_b128 v[236:239], v108 offset:320
	s_waitcnt lgkmcnt(0)
	v_pk_mul_f32 v[44:45], v[12:13], v[236:237]
	v_pk_mul_f32 v[46:47], v[14:15], v[238:239]
	v_cvt_pk_bf16_f32 v44, v44, v45
	v_cvt_pk_bf16_f32 v45, v46, v47
	ds_write_b64 v52, v[44:45] offset:45216
	ds_read_b128 v[244:247], v108 offset:384
	s_waitcnt lgkmcnt(0)
	v_pk_mul_f32 v[44:45], v[24:25], v[244:245]
	v_pk_mul_f32 v[46:47], v[26:27], v[246:247]
	v_cvt_pk_bf16_f32 v44, v44, v45
	v_cvt_pk_bf16_f32 v45, v46, v47
	ds_write_b64 v52, v[44:45] offset:45248
	ds_read_b128 v[248:251], v108 offset:448
	s_waitcnt lgkmcnt(0)
	v_pk_mul_f32 v[44:45], v[28:29], v[248:249]
	v_pk_mul_f32 v[46:47], v[30:31], v[250:251]
	v_cvt_pk_bf16_f32 v44, v44, v45
	v_cvt_pk_bf16_f32 v45, v46, v47
	ds_write_b64 v52, v[44:45] offset:45280
	ds_read_b128 v[252:255], v119 offset:17408
	ds_read_b128 v[216:219], v119 offset:17472
	ds_read_b128 v[220:223], v119 offset:21824
	ds_read_b128 v[224:227], v119 offset:17536
	ds_read_b128 v[228:231], v119 offset:17600
	ds_read_b128 v[232:235], v119 offset:21760
	v_add_u32_e32 v44, v109, v107
	ds_read_b128 v[60:63], v44
	ds_read_b128 v[52:55], v44 offset:64
	ds_read_b128 v[56:59], v44 offset:128
	ds_read_b128 v[44:47], v44 offset:192
	s_waitcnt lgkmcnt(3)
	v_mfma_f32_16x16x32_bf16 v[96:99], v[252:255], v[60:63], 0
	ds_read_b128 v[236:239], v119 offset:21888
	s_waitcnt lgkmcnt(3)
	v_mfma_f32_16x16x32_bf16 v[96:99], v[216:219], v[52:55], v[96:99]
	ds_read_b128 v[244:247], v119 offset:21952
	s_waitcnt lgkmcnt(3)
	v_mfma_f32_16x16x32_bf16 v[96:99], v[224:227], v[56:59], v[96:99]
	ds_read_b128 v[248:251], v119 offset:26176
	s_waitcnt lgkmcnt(3)
	v_mfma_f32_16x16x32_bf16 v[96:99], v[228:231], v[44:47], v[96:99]
	ds_read_b128 v[252:255], v119 offset:26112
	s_nop 6
	v_cndmask_b32_e64 v66, v96, 0, s[8:9]
	v_mfma_f32_16x16x32_bf16 v[160:163], v[232:235], v[60:63], 0
	ds_read_b128 v[216:219], v119 offset:26240
	v_cndmask_b32_e64 v75, v97, 0, s[10:11]
	v_cndmask_b32_e64 v95, v98, 0, s[12:13]
	v_cndmask_b32_e64 v97, v99, 0, s[14:15]
	v_mfma_f32_16x16x32_bf16 v[160:163], v[220:223], v[52:55], v[160:163]
	ds_read_b128 v[224:227], v119 offset:26304
	v_cvt_pk_bf16_f32 v96, v66, v75
	v_cvt_pk_bf16_f32 v97, v95, v97
	s_waitcnt lgkmcnt(5)
	v_mfma_f32_16x16x32_bf16 v[160:163], v[236:239], v[56:59], v[160:163]
	ds_read_b128 v[228:231], v119 offset:30528
	s_waitcnt lgkmcnt(5)
	v_mfma_f32_16x16x32_bf16 v[160:163], v[244:247], v[44:47], v[160:163]
	ds_read_b128 v[232:235], v119 offset:30464
	s_nop 6
	v_cndmask_b32_e64 v66, v160, 0, s[16:17]
	v_cndmask_b32_e64 v75, v161, 0, s[18:19]
	v_cndmask_b32_e64 v95, v162, 0, s[20:21]
	v_cndmask_b32_e64 v99, v163, 0, s[22:23]
	s_waitcnt lgkmcnt(4)
	v_mfma_f32_16x16x32_bf16 v[160:163], v[252:255], v[60:63], 0
	ds_read_b128 v[220:223], v119 offset:30592
	v_cvt_pk_bf16_f32 v98, v66, v75
	v_cvt_pk_bf16_f32 v99, v95, v99
	v_mfma_f32_16x16x32_bf16 v[160:163], v[248:251], v[52:55], v[160:163]
	s_waitcnt lgkmcnt(4)
	v_mfma_f32_16x16x32_bf16 v[160:163], v[216:219], v[56:59], v[160:163]
	s_waitcnt lgkmcnt(3)
	v_mfma_f32_16x16x32_bf16 v[160:163], v[224:227], v[44:47], v[160:163]
	s_nop 6
	s_nop 0
	v_cndmask_b32_e64 v66, v160, 0, s[24:25]
	v_cndmask_b32_e64 v95, v162, 0, s[28:29]
	v_cndmask_b32_e64 v160, v163, 0, s[30:31]
	v_cndmask_b32_e64 v75, v161, 0, s[26:27]
	v_cvt_pk_bf16_f32 v169, v95, v160
	s_waitcnt lgkmcnt(1)
	v_mfma_f32_16x16x32_bf16 v[160:163], v[232:235], v[60:63], 0
	v_cvt_pk_bf16_f32 v168, v66, v75
	v_mfma_f32_16x16x32_bf16 v[160:163], v[228:231], v[52:55], v[160:163]
	s_waitcnt lgkmcnt(0)
	v_mfma_f32_16x16x32_bf16 v[160:163], v[220:223], v[56:59], v[160:163]
	ds_read_b128 v[164:167], v119 offset:30656
	s_waitcnt lgkmcnt(0)
	s_barrier
	v_mfma_f32_16x16x32_bf16 v[160:163], v[164:167], v[44:47], v[160:163]
	s_nop 7
	v_cndmask_b32_e64 v66, v160, 0, s[34:35]
	v_cndmask_b32_e64 v75, v161, 0, s[36:37]
	v_cvt_pk_bf16_f32 v160, v66, v75
	v_add_u32_e32 v66, v110, v111
	v_cndmask_b32_e64 v95, v162, 0, s[38:39]
	v_cndmask_b32_e64 v161, v163, 0, s[40:41]
	v_add_u32_e32 v66, 0xf000, v66
	v_cvt_pk_bf16_f32 v161, v95, v161
	ds_write2_b64 v66, v[96:97], v[98:99] offset0:128 offset1:132
	ds_write2_b64 v66, v[168:169], v[160:161] offset0:136 offset1:140
	ds_write_b128 v120, v[48:51] offset:17408
	ds_write_b128 v120, v[36:39] offset:17424
	ds_write_b128 v120, v[40:43] offset:17552
	ds_write_b128 v120, v[32:35] offset:17568
	v_add_u32_e32 v160, v110, v107
	s_waitcnt lgkmcnt(0)
	s_barrier
	s_waitcnt lgkmcnt(0)
	ds_read_b128 v[216:219], v160 offset:62464
	ds_read_b128 v[220:223], v160 offset:62528
	ds_read_b128 v[224:227], v121 offset:35840
	ds_read_b128 v[228:231], v121 offset:35904
	ds_read_b128 v[232:235], v119 offset:45056
	ds_read_b128 v[236:239], v119 offset:45120
	s_waitcnt lgkmcnt(3)
	v_mfma_f32_16x16x32_bf16 v[48:51], v[224:227], v[216:219], 0
	ds_read_b128 v[244:247], v119 offset:45184
	ds_read_b128 v[248:251], v119 offset:45248
	v_ashrrev_i32_e32 v40, 9, v71
	v_cmp_gt_i32_e32 vcc, 32, v40
	v_lshlrev_b32_e32 v40, 1, v40
	s_waitcnt lgkmcnt(4)
	v_mfma_f32_16x16x32_bf16 v[48:51], v[228:231], v[220:223], v[48:51]
	ds_read_b128 v[252:255], v121 offset:38144
	ds_read_b128 v[224:227], v121 offset:38208
	v_subrev_u32_e32 v42, 63, v40
	v_or_b32_e32 v40, 1, v40
	s_waitcnt lgkmcnt(5)
	v_mfma_f32_16x16x32_bf16 v[48:51], v[232:235], v[60:63], v[48:51]
	ds_read_b128 v[228:231], v119 offset:49408
	v_ashrrev_i32_e32 v41, 31, v40
	v_cndmask_b32_e32 v41, 0, v41, vcc
	s_waitcnt lgkmcnt(5)
	v_mfma_f32_16x16x32_bf16 v[48:51], v[236:239], v[52:55], v[48:51]
	ds_read_b128 v[232:235], v119 offset:49472
	v_cndmask_b32_e32 v40, v42, v40, vcc
	v_cndmask_b32_e32 v66, v122, v123, vcc
	s_waitcnt lgkmcnt(5)
	v_mfma_f32_16x16x32_bf16 v[48:51], v[244:247], v[56:59], v[48:51]
	ds_read_b128 v[236:239], v119 offset:49536
	v_lshl_add_u64 v[42:43], s[94:95], 0, v[66:67]
	v_lshlrev_b64 v[40:41], 20, v[40:41]
	s_waitcnt lgkmcnt(5)
	v_mfma_f32_16x16x32_bf16 v[48:51], v[248:251], v[44:47], v[48:51]
	ds_read_b128 v[244:247], v119 offset:49600
	v_lshl_add_u64 v[40:41], v[42:43], 0, v[40:41]
	v_and_b32_e32 v42, 0x7fc00, v73
	v_lshlrev_b32_e32 v66, 1, v42
	s_nop 4
	v_cvt_pk_bf16_f32 v42, v48, v49
	v_cvt_pk_bf16_f32 v43, v50, v51
	s_waitcnt lgkmcnt(5)
	v_mfma_f32_16x16x32_bf16 v[48:51], v[252:255], v[216:219], 0
	ds_read_b128 v[248:251], v121 offset:40512
	v_lshl_add_u64 v[40:41], v[40:41], 0, v[66:67]
	v_mov_b32_e32 v95, v67
	v_lshl_add_u64 v[40:41], v[40:41], 0, v[94:95]
	s_waitcnt lgkmcnt(5)
	v_mfma_f32_16x16x32_bf16 v[48:51], v[224:227], v[220:223], v[48:51]
	ds_read_b128 v[252:255], v121 offset:40448
	v_lshl_add_u64 v[40:41], v[80:81], 1, v[40:41]
	v_mov_b32_e32 v75, v67
	s_waitcnt lgkmcnt(5)
	v_mfma_f32_16x16x32_bf16 v[48:51], v[228:231], v[60:63], v[48:51]
	ds_read_b128 v[224:227], v119 offset:53760
	v_lshl_add_u64 v[40:41], v[40:41], 0, v[74:75]
	global_store_dwordx2 v[40:41], v[42:43], off
	s_waitcnt lgkmcnt(5)
	v_mfma_f32_16x16x32_bf16 v[48:51], v[232:235], v[52:55], v[48:51]
	ds_read_b128 v[228:231], v119 offset:53824
	v_cmp_eq_u32_e32 vcc, -2, v92
	v_add_u32_e32 v73, 0xffff0000, v73
	s_waitcnt lgkmcnt(5)
	v_mfma_f32_16x16x32_bf16 v[48:51], v[236:239], v[56:59], v[48:51]
	ds_read_b128 v[232:235], v119 offset:53888
	v_subrev_u32_e32 v71, 64, v71
	s_or_b64 s[56:57], vcc, s[56:57]
	s_waitcnt lgkmcnt(5)
	v_mfma_f32_16x16x32_bf16 v[48:51], v[244:247], v[44:47], v[48:51]
	ds_read_b128 v[236:239], v121 offset:42752
	s_nop 6
	v_cvt_pk_bf16_f32 v42, v48, v49
	v_cvt_pk_bf16_f32 v43, v50, v51
	s_waitcnt lgkmcnt(4)
	v_mfma_f32_16x16x32_bf16 v[48:51], v[252:255], v[216:219], 0
	ds_read_b128 v[244:247], v119 offset:58112
	global_store_dwordx2 v[40:41], v[42:43], off offset:32
	v_mfma_f32_16x16x32_bf16 v[48:51], v[248:251], v[220:223], v[48:51]
	ds_read_b128 v[252:255], v119 offset:58176
	s_waitcnt lgkmcnt(5)
	v_mfma_f32_16x16x32_bf16 v[48:51], v[224:227], v[60:63], v[48:51]
	ds_read_b128 v[248:251], v119 offset:58240
	s_waitcnt lgkmcnt(5)
	v_mfma_f32_16x16x32_bf16 v[48:51], v[228:231], v[52:55], v[48:51]
	ds_read_b128 v[224:227], v119 offset:58304
	s_waitcnt lgkmcnt(5)
	v_mfma_f32_16x16x32_bf16 v[48:51], v[232:235], v[56:59], v[48:51]
	ds_read_b128 v[228:231], v112
	ds_read_b128 v[96:99], v119 offset:53952
	s_waitcnt lgkmcnt(0)
	v_mfma_f32_16x16x32_bf16 v[48:51], v[96:99], v[44:47], v[48:51]
	s_nop 7
	v_cvt_pk_bf16_f32 v42, v48, v49
	v_cvt_pk_bf16_f32 v43, v50, v51
	v_mfma_f32_16x16x32_bf16 v[36:39], v[236:239], v[216:219], 0
	ds_read_b128 v[232:235], v121 offset:17408
	ds_read_b128 v[48:51], v121 offset:42816
	global_store_dwordx2 v[40:41], v[42:43], off offset:64
	s_waitcnt lgkmcnt(0)
	v_mfma_f32_16x16x32_bf16 v[32:35], v[48:51], v[220:223], v[36:39]
	s_nop 3
	v_mfma_f32_16x16x32_bf16 v[32:35], v[244:247], v[60:63], v[32:35]
	ds_read_b128 v[216:219], v121 offset:17472
	v_mfma_f32_16x16x32_bf16 v[32:35], v[252:255], v[52:55], v[32:35]
	ds_read_b128 v[236:239], v112 offset:64
	v_mfma_f32_16x16x32_bf16 v[32:35], v[248:251], v[56:59], v[32:35]
	ds_read_b128 v[220:223], v121 offset:19712
	v_mfma_f32_16x16x32_bf16 v[32:35], v[224:227], v[44:47], v[32:35]
	ds_read_b128 v[244:247], v121 offset:19776
	s_nop 7
	v_cvt_pk_bf16_f32 v32, v32, v33
	v_cvt_pk_bf16_f32 v33, v34, v35
	global_store_dwordx2 v[40:41], v[32:33], off offset:96
	ds_read_b128 v[36:39], v160 offset:35840
	ds_read_b128 v[32:35], v160 offset:35904
	v_pk_mul_f32 v[16:17], v[16:17], v[228:229]
	ds_read_b128 v[252:255], v112 offset:128
	v_pk_mul_f32 v[18:19], v[18:19], v[230:231]
	s_waitcnt lgkmcnt(2)
	s_nop 0
	v_mfma_f32_16x16x32_bf16 v[16:19], v[232:235], v[36:39], v[16:19]
	ds_read_b128 v[248:251], v121 offset:22016
	s_waitcnt lgkmcnt(2)
	v_mfma_f32_16x16x32_bf16 v[16:19], v[216:219], v[32:35], v[16:19]
	ds_read_b128 v[224:227], v121 offset:22080
	v_pk_mul_f32 v[0:1], v[0:1], v[236:237]
	ds_read_b128 v[228:231], v112 offset:192
	v_pk_mul_f32 v[2:3], v[2:3], v[238:239]
	s_nop 1
	v_mfma_f32_16x16x32_bf16 v[0:3], v[220:223], v[36:39], v[0:3]
	ds_read_b128 v[232:235], v121 offset:24320
	v_mfma_f32_16x16x32_bf16 v[0:3], v[244:247], v[32:35], v[0:3]
	ds_read_b128 v[216:219], v121 offset:24384
	s_waitcnt lgkmcnt(5)
	v_pk_mul_f32 v[8:9], v[8:9], v[252:253]
	ds_read_b128 v[236:239], v112 offset:256
	v_pk_mul_f32 v[10:11], v[10:11], v[254:255]
	s_waitcnt lgkmcnt(5)
	s_nop 0
	v_mfma_f32_16x16x32_bf16 v[8:11], v[248:251], v[36:39], v[8:11]
	ds_read_b128 v[220:223], v121 offset:26624
	s_waitcnt lgkmcnt(5)
	v_mfma_f32_16x16x32_bf16 v[8:11], v[224:227], v[32:35], v[8:11]
	ds_read_b128 v[244:247], v121 offset:26688
	s_waitcnt lgkmcnt(5)
	v_pk_mul_f32 v[4:5], v[4:5], v[228:229]
	ds_read_b128 v[252:255], v112 offset:320
	v_pk_mul_f32 v[6:7], v[6:7], v[230:231]
	s_waitcnt lgkmcnt(5)
	s_nop 0
	v_mfma_f32_16x16x32_bf16 v[4:7], v[232:235], v[36:39], v[4:7]
	ds_read_b128 v[248:251], v121 offset:28928
	s_waitcnt lgkmcnt(5)
	v_mfma_f32_16x16x32_bf16 v[4:7], v[216:219], v[32:35], v[4:7]
	ds_read_b128 v[224:227], v121 offset:28992
	s_waitcnt lgkmcnt(5)
	v_pk_mul_f32 v[20:21], v[20:21], v[236:237]
	ds_read_b128 v[228:231], v112 offset:384
	v_pk_mul_f32 v[22:23], v[22:23], v[238:239]
	s_waitcnt lgkmcnt(5)
	s_nop 0
	v_mfma_f32_16x16x32_bf16 v[20:23], v[220:223], v[36:39], v[20:23]
	ds_read_b128 v[232:235], v121 offset:31232
	s_waitcnt lgkmcnt(5)
	v_mfma_f32_16x16x32_bf16 v[20:23], v[244:247], v[32:35], v[20:23]
	ds_read_b128 v[216:219], v121 offset:31296
	s_waitcnt lgkmcnt(5)
	v_pk_mul_f32 v[12:13], v[12:13], v[252:253]
	ds_read_b128 v[236:239], v112 offset:448
	v_pk_mul_f32 v[14:15], v[14:15], v[254:255]
	s_waitcnt lgkmcnt(5)
	s_nop 0
	v_mfma_f32_16x16x32_bf16 v[12:15], v[248:251], v[36:39], v[12:15]
	s_waitcnt lgkmcnt(4)
	v_mfma_f32_16x16x32_bf16 v[12:15], v[224:227], v[32:35], v[12:15]
	s_waitcnt lgkmcnt(3)
	v_pk_mul_f32 v[24:25], v[24:25], v[228:229]
	v_pk_mul_f32 v[26:27], v[26:27], v[230:231]
	s_waitcnt lgkmcnt(2)
	s_nop 0
	v_mfma_f32_16x16x32_bf16 v[24:27], v[232:235], v[36:39], v[24:27]
	s_waitcnt lgkmcnt(1)
	v_mfma_f32_16x16x32_bf16 v[24:27], v[216:219], v[32:35], v[24:27]
	s_waitcnt lgkmcnt(0)
	v_pk_mul_f32 v[28:29], v[28:29], v[236:237]
	v_pk_mul_f32 v[30:31], v[30:31], v[238:239]
	ds_read_b128 v[40:43], v121 offset:33536
	s_waitcnt lgkmcnt(0)
	v_mfma_f32_16x16x32_bf16 v[28:31], v[40:43], v[36:39], v[28:31]
	ds_read_b128 v[36:39], v121 offset:33600
	s_waitcnt lgkmcnt(0)
	s_barrier
	v_mfma_f32_16x16x32_bf16 v[28:31], v[36:39], v[32:35], v[28:31]
	s_andn2_b64 exec, exec, s[56:57]
	s_cbranch_execz .LBB0_1466

.LBB0_1476:
	s_or_b64 exec, exec, s[60:61]
	v_sub_f32_e32 v32, v73, v33
	v_exp_f32_e32 v156, v32
	v_sub_f32_e32 v32, v155, v35
	v_exp_f32_e32 v158, v32
	v_mov_b32_e32 v32, v36
	v_mov_b32_e32 v33, v38
	v_mov_b32_e32 v38, v37
	v_pk_mul_f32 v[32:33], v[156:157], v[32:33] op_sel_hi:[0,1]
	v_pk_mul_f32 v[34:35], v[158:159], v[38:39] op_sel_hi:[0,1]
	v_cvt_pk_bf16_f32 v36, v32, v33
	v_cvt_pk_bf16_f32 v32, v34, v35
	v_mov_b32_e32 v34, v40
	v_mov_b32_e32 v35, v42
	v_pk_mul_f32 v[34:35], v[156:157], v[34:35] op_sel_hi:[0,1]
	v_mov_b32_e32 v42, v41
	v_cvt_pk_bf16_f32 v37, v34, v35
	v_mov_b32_e32 v34, v44
	v_mov_b32_e32 v35, v46
	v_mov_b32_e32 v46, v45
	v_pk_mul_f32 v[38:39], v[158:159], v[42:43] op_sel_hi:[0,1]
	v_pk_mul_f32 v[34:35], v[156:157], v[34:35] op_sel_hi:[0,1]
	v_pk_mul_f32 v[40:41], v[158:159], v[46:47] op_sel_hi:[0,1]
	v_cvt_pk_bf16_f32 v33, v38, v39
	v_cvt_pk_bf16_f32 v38, v34, v35
	v_cvt_pk_bf16_f32 v34, v40, v41
	v_mov_b32_e32 v40, v48
	v_mov_b32_e32 v41, v50
	v_pk_mul_f32 v[40:41], v[156:157], v[40:41] op_sel_hi:[0,1]
	v_mov_b32_e32 v50, v49
	v_pk_mul_f32 v[42:43], v[158:159], v[50:51] op_sel_hi:[0,1]
	v_cvt_pk_bf16_f32 v39, v40, v41
	v_mov_b32_e32 v40, v52
	v_mov_b32_e32 v41, v54
	v_mov_b32_e32 v54, v53
	v_cvt_pk_bf16_f32 v35, v42, v43
	v_pk_mul_f32 v[40:41], v[156:157], v[40:41] op_sel_hi:[0,1]
	v_pk_mul_f32 v[42:43], v[158:159], v[54:55] op_sel_hi:[0,1]
	v_cvt_pk_bf16_f32 v44, v40, v41
	v_cvt_pk_bf16_f32 v40, v42, v43
	v_mov_b32_e32 v42, v56
	v_mov_b32_e32 v43, v60
	v_pk_mul_f32 v[42:43], v[156:157], v[42:43] op_sel_hi:[0,1]
	v_mov_b32_e32 v60, v57
	v_cvt_pk_bf16_f32 v45, v42, v43
	v_mov_b32_e32 v42, v92
	v_mov_b32_e32 v43, v94
	v_mov_b32_e32 v94, v93
	v_pk_mul_f32 v[46:47], v[158:159], v[60:61] op_sel_hi:[0,1]
	v_pk_mul_f32 v[42:43], v[156:157], v[42:43] op_sel_hi:[0,1]
	v_pk_mul_f32 v[48:49], v[158:159], v[94:95] op_sel_hi:[0,1]
	v_cvt_pk_bf16_f32 v41, v46, v47
	v_cvt_pk_bf16_f32 v46, v42, v43
	v_cvt_pk_bf16_f32 v42, v48, v49
	v_mov_b32_e32 v48, v62
	v_mov_b32_e32 v49, v58
	v_mov_b32_e32 v58, v63
	v_pk_mul_f32 v[48:49], v[156:157], v[48:49] op_sel_hi:[0,1]
	v_pk_mul_f32 v[50:51], v[158:159], v[58:59] op_sel_hi:[0,1]
	v_cvt_pk_bf16_f32 v47, v48, v49
	v_cvt_pk_bf16_f32 v43, v50, v51
	s_waitcnt lgkmcnt(0)
	s_barrier
	s_waitcnt lgkmcnt(0)
	ds_read_b128 v[216:219], v105
	v_add_u32_e32 v52, v107, v109
	v_add_u32_e32 v60, v107, v104
	v_cmp_eq_u32_e32 vcc, s75, v132
	v_lshl_add_u64 v[86:87], v[86:87], 0, s[56:57]
	s_waitcnt lgkmcnt(0)
	v_pk_mul_f32 v[48:49], v[12:13], v[216:217]
	v_pk_mul_f32 v[50:51], v[14:15], v[218:219]
	v_cvt_pk_bf16_f32 v48, v48, v49
	v_cvt_pk_bf16_f32 v49, v50, v51
	ds_write_b64 v52, v[48:49] offset:45056
	ds_read_b128 v[220:223], v105 offset:64
	v_lshl_add_u64 v[88:89], v[88:89], 0, s[56:57]
	v_lshl_add_u64 v[90:91], v[90:91], 0, s[56:57]
	s_or_b64 s[58:59], vcc, s[58:59]
	s_waitcnt lgkmcnt(0)
	v_pk_mul_f32 v[48:49], v[0:1], v[220:221]
	v_pk_mul_f32 v[50:51], v[2:3], v[222:223]
	v_cvt_pk_bf16_f32 v48, v48, v49
	v_cvt_pk_bf16_f32 v49, v50, v51
	ds_write_b64 v113, v[48:49] offset:45056
	ds_read_b128 v[224:227], v105 offset:128
	s_waitcnt lgkmcnt(0)
	v_pk_mul_f32 v[48:49], v[8:9], v[224:225]
	v_pk_mul_f32 v[50:51], v[10:11], v[226:227]
	v_cvt_pk_bf16_f32 v48, v48, v49
	v_cvt_pk_bf16_f32 v49, v50, v51
	ds_write_b64 v114, v[48:49] offset:45056
	ds_read_b128 v[228:231], v105 offset:192
	s_waitcnt lgkmcnt(0)
	v_pk_mul_f32 v[48:49], v[4:5], v[228:229]
	v_pk_mul_f32 v[50:51], v[6:7], v[230:231]
	v_cvt_pk_bf16_f32 v48, v48, v49
	v_cvt_pk_bf16_f32 v49, v50, v51
	ds_write_b64 v115, v[48:49] offset:45056
	ds_read_b128 v[232:235], v105 offset:256
	s_waitcnt lgkmcnt(0)
	v_pk_mul_f32 v[48:49], v[20:21], v[232:233]
	v_pk_mul_f32 v[50:51], v[22:23], v[234:235]
	v_cvt_pk_bf16_f32 v48, v48, v49
	v_cvt_pk_bf16_f32 v49, v50, v51
	ds_write_b64 v52, v[48:49] offset:45184
	ds_read_b128 v[236:239], v105 offset:320
	s_waitcnt lgkmcnt(0)
	v_pk_mul_f32 v[48:49], v[16:17], v[236:237]
	v_pk_mul_f32 v[50:51], v[18:19], v[238:239]
	v_cvt_pk_bf16_f32 v48, v48, v49
	v_cvt_pk_bf16_f32 v49, v50, v51
	ds_write_b64 v52, v[48:49] offset:45216
	ds_read_b128 v[244:247], v105 offset:384
	s_waitcnt lgkmcnt(0)
	v_pk_mul_f32 v[48:49], v[24:25], v[244:245]
	v_pk_mul_f32 v[50:51], v[26:27], v[246:247]
	v_cvt_pk_bf16_f32 v48, v48, v49
	v_cvt_pk_bf16_f32 v49, v50, v51
	ds_write_b64 v52, v[48:49] offset:45248
	ds_read_b128 v[248:251], v105 offset:448
	s_waitcnt lgkmcnt(0)
	v_pk_mul_f32 v[48:49], v[28:29], v[248:249]
	v_pk_mul_f32 v[50:51], v[30:31], v[250:251]
	v_cvt_pk_bf16_f32 v48, v48, v49
	v_cvt_pk_bf16_f32 v49, v50, v51
	ds_write_b64 v52, v[48:49] offset:45280
	ds_read_b128 v[252:255], v116 offset:17408
	ds_read_b128 v[216:219], v116 offset:17472
	ds_read_b128 v[220:223], v116 offset:21824
	ds_read_b128 v[224:227], v116 offset:17536
	ds_read_b128 v[228:231], v116 offset:17600
	ds_read_b128 v[232:235], v116 offset:21760
	ds_read_b128 v[48:51], v60
	ds_read_b128 v[52:55], v60 offset:64
	ds_read_b128 v[56:59], v60 offset:128
	ds_read_b128 v[60:63], v60 offset:192
	s_waitcnt lgkmcnt(3)
	v_mfma_f32_16x16x32_bf16 v[92:95], v[252:255], v[48:51], 0
	ds_read_b128 v[236:239], v116 offset:21888
	s_waitcnt lgkmcnt(3)
	v_mfma_f32_16x16x32_bf16 v[92:95], v[216:219], v[52:55], v[92:95]
	ds_read_b128 v[244:247], v116 offset:21952
	s_waitcnt lgkmcnt(3)
	v_mfma_f32_16x16x32_bf16 v[92:95], v[224:227], v[56:59], v[92:95]
	ds_read_b128 v[248:251], v116 offset:26176
	s_waitcnt lgkmcnt(3)
	v_mfma_f32_16x16x32_bf16 v[92:95], v[228:231], v[60:63], v[92:95]
	ds_read_b128 v[252:255], v116 offset:26112
	s_nop 6
	v_cndmask_b32_e64 v73, v92, 0, s[4:5]
	v_mfma_f32_16x16x32_bf16 v[156:159], v[232:235], v[48:51], 0
	ds_read_b128 v[216:219], v116 offset:26240
	v_cndmask_b32_e64 v92, 0, v93, s[6:7]
	v_cndmask_b32_e64 v93, v94, 0, s[8:9]
	v_cndmask_b32_e64 v94, v95, 0, s[10:11]
	v_mfma_f32_16x16x32_bf16 v[156:159], v[220:223], v[52:55], v[156:159]
	ds_read_b128 v[224:227], v116 offset:26304
	v_cvt_pk_bf16_f32 v92, v73, v92
	v_cvt_pk_bf16_f32 v93, v93, v94
	s_waitcnt lgkmcnt(5)
	v_mfma_f32_16x16x32_bf16 v[156:159], v[236:239], v[56:59], v[156:159]
	ds_read_b128 v[228:231], v116 offset:30528
	s_waitcnt lgkmcnt(5)
	v_mfma_f32_16x16x32_bf16 v[156:159], v[244:247], v[60:63], v[156:159]
	ds_read_b128 v[232:235], v116 offset:30464
	s_nop 6
	v_cndmask_b32_e64 v73, v156, 0, s[12:13]
	v_cndmask_b32_e64 v94, v157, 0, s[14:15]
	v_cndmask_b32_e64 v95, v158, 0, s[16:17]
	v_cndmask_b32_e64 v155, v159, 0, s[18:19]
	s_waitcnt lgkmcnt(4)
	v_mfma_f32_16x16x32_bf16 v[156:159], v[252:255], v[48:51], 0
	ds_read_b128 v[220:223], v116 offset:30592
	v_cvt_pk_bf16_f32 v94, v73, v94
	v_cvt_pk_bf16_f32 v95, v95, v155
	v_mfma_f32_16x16x32_bf16 v[156:159], v[248:251], v[52:55], v[156:159]
	s_waitcnt lgkmcnt(4)
	v_mfma_f32_16x16x32_bf16 v[156:159], v[216:219], v[56:59], v[156:159]
	s_waitcnt lgkmcnt(3)
	v_mfma_f32_16x16x32_bf16 v[156:159], v[224:227], v[60:63], v[156:159]
	s_nop 6
	s_nop 0
	v_cndmask_b32_e64 v73, v156, 0, s[20:21]
	v_cndmask_b32_e64 v155, v157, 0, s[22:23]
	v_cndmask_b32_e64 v156, v158, 0, s[24:25]
	v_cndmask_b32_e64 v157, v159, 0, s[26:27]
	v_cvt_pk_bf16_f32 v165, v156, v157
	s_waitcnt lgkmcnt(1)
	v_mfma_f32_16x16x32_bf16 v[156:159], v[232:235], v[48:51], 0
	v_cvt_pk_bf16_f32 v164, v73, v155
	v_mfma_f32_16x16x32_bf16 v[156:159], v[228:231], v[52:55], v[156:159]
	s_waitcnt lgkmcnt(0)
	v_mfma_f32_16x16x32_bf16 v[156:159], v[220:223], v[56:59], v[156:159]
	ds_read_b128 v[160:163], v116 offset:30656
	s_waitcnt lgkmcnt(0)
	s_barrier
	v_mfma_f32_16x16x32_bf16 v[156:159], v[160:163], v[60:63], v[156:159]
	s_nop 7
	v_cndmask_b32_e64 v73, v156, 0, s[28:29]
	v_cndmask_b32_e64 v155, v157, 0, s[30:31]
	v_cvt_pk_bf16_f32 v156, v73, v155
	v_add_u32_e32 v73, v108, v109
	v_cndmask_b32_e64 v157, v158, 0, s[34:35]
	v_cndmask_b32_e64 v158, v159, 0, s[36:37]
	v_add_u32_e32 v73, 0xf000, v73
	v_cvt_pk_bf16_f32 v157, v157, v158
	ds_write2_b64 v73, v[92:93], v[94:95] offset0:128 offset1:132
	ds_write2_b64 v73, v[164:165], v[156:157] offset0:136 offset1:140
	ds_write_b128 v117, v[36:39] offset:17408
	ds_write_b128 v117, v[44:47] offset:17424
	ds_write_b128 v117, v[32:35] offset:17552
	ds_write_b128 v117, v[40:43] offset:17568
	v_add_u32_e32 v46, v108, v104
	s_waitcnt lgkmcnt(0)
	s_barrier
	s_waitcnt lgkmcnt(0)
	ds_read_b128 v[216:219], v46 offset:62464
	ds_read_b128 v[220:223], v46 offset:62528
	ds_read_b128 v[224:227], v118 offset:35840
	ds_read_b128 v[228:231], v118 offset:35904
	ds_read_b128 v[232:235], v116 offset:45056
	ds_read_b128 v[236:239], v116 offset:45120
	s_waitcnt lgkmcnt(3)
	v_mfma_f32_16x16x32_bf16 v[42:45], v[224:227], v[216:219], 0
	ds_read_b128 v[244:247], v116 offset:45184
	ds_read_b128 v[248:251], v116 offset:45248
	v_lshlrev_b64 v[32:33], 11, v[64:65]
	v_lshl_add_u64 v[32:33], v[84:85], 0, v[32:33]
	v_add_u32_e32 v64, 64, v64
	s_waitcnt lgkmcnt(4)
	v_mfma_f32_16x16x32_bf16 v[42:45], v[228:231], v[220:223], v[42:45]
	ds_read_b128 v[252:255], v118 offset:38208
	ds_read_b128 v[224:227], v118 offset:38144
	s_waitcnt lgkmcnt(5)
	v_mfma_f32_16x16x32_bf16 v[42:45], v[232:235], v[48:51], v[42:45]
	ds_read_b128 v[228:231], v116 offset:49408
	s_waitcnt lgkmcnt(5)
	v_mfma_f32_16x16x32_bf16 v[42:45], v[236:239], v[52:55], v[42:45]
	ds_read_b128 v[232:235], v116 offset:49472
	s_waitcnt lgkmcnt(5)
	v_mfma_f32_16x16x32_bf16 v[42:45], v[244:247], v[56:59], v[42:45]
	ds_read_b128 v[236:239], v116 offset:49536
	s_waitcnt lgkmcnt(5)
	v_mfma_f32_16x16x32_bf16 v[42:45], v[248:251], v[60:63], v[42:45]
	ds_read_b128 v[244:247], v116 offset:49600
	s_nop 6
	v_cvt_pk_bf16_f32 v42, v42, v43
	v_cvt_pk_bf16_f32 v43, v44, v45
	global_store_dwordx2 v[32:33], v[42:43], off
	s_waitcnt lgkmcnt(4)
	v_mfma_f32_16x16x32_bf16 v[42:45], v[224:227], v[216:219], 0
	ds_read_b128 v[248:251], v118 offset:40512
	v_mfma_f32_16x16x32_bf16 v[42:45], v[252:255], v[220:223], v[42:45]
	ds_read_b128 v[224:227], v118 offset:40448
	s_waitcnt lgkmcnt(5)
	v_mfma_f32_16x16x32_bf16 v[42:45], v[228:231], v[48:51], v[42:45]
	ds_read_b128 v[252:255], v116 offset:53760
	s_waitcnt lgkmcnt(5)
	v_mfma_f32_16x16x32_bf16 v[42:45], v[232:235], v[52:55], v[42:45]
	ds_read_b128 v[228:231], v116 offset:53824
	s_waitcnt lgkmcnt(5)
	v_mfma_f32_16x16x32_bf16 v[42:45], v[236:239], v[56:59], v[42:45]
	ds_read_b128 v[232:235], v116 offset:53888
	s_waitcnt lgkmcnt(5)
	v_mfma_f32_16x16x32_bf16 v[42:45], v[244:247], v[60:63], v[42:45]
	ds_read_b128 v[236:239], v118 offset:42752
	s_nop 6
	v_cvt_pk_bf16_f32 v42, v42, v43
	v_cvt_pk_bf16_f32 v43, v44, v45
	global_store_dwordx2 v[32:33], v[42:43], off offset:32
	s_waitcnt lgkmcnt(4)
	v_mfma_f32_16x16x32_bf16 v[42:45], v[224:227], v[216:219], 0
	ds_read_b128 v[244:247], v116 offset:58112
	v_mfma_f32_16x16x32_bf16 v[42:45], v[248:251], v[220:223], v[42:45]
	ds_read_b128 v[224:227], v116 offset:58176
	s_waitcnt lgkmcnt(5)
	v_mfma_f32_16x16x32_bf16 v[42:45], v[252:255], v[48:51], v[42:45]
	ds_read_b128 v[248:251], v116 offset:58240
	s_waitcnt lgkmcnt(5)
	v_mfma_f32_16x16x32_bf16 v[42:45], v[228:231], v[52:55], v[42:45]
	ds_read_b128 v[252:255], v116 offset:58304
	s_waitcnt lgkmcnt(5)
	v_mfma_f32_16x16x32_bf16 v[42:45], v[232:235], v[56:59], v[42:45]
	ds_read_b128 v[228:231], v110
	ds_read_b128 v[92:95], v116 offset:53952
	s_waitcnt lgkmcnt(0)
	v_mfma_f32_16x16x32_bf16 v[42:45], v[92:95], v[60:63], v[42:45]
	s_nop 7
	v_cvt_pk_bf16_f32 v42, v42, v43
	v_cvt_pk_bf16_f32 v43, v44, v45
	global_store_dwordx2 v[32:33], v[42:43], off offset:64
	v_mfma_f32_16x16x32_bf16 v[34:37], v[236:239], v[216:219], 0
	ds_read_b128 v[232:235], v118 offset:17408
	ds_read_b128 v[42:45], v118 offset:42816
	s_waitcnt lgkmcnt(0)
	v_mfma_f32_16x16x32_bf16 v[34:37], v[42:45], v[220:223], v[34:37]
	v_mfma_f32_16x16x32_bf16 v[34:37], v[244:247], v[48:51], v[34:37]
	ds_read_b128 v[216:219], v118 offset:17472
	v_mfma_f32_16x16x32_bf16 v[34:37], v[224:227], v[52:55], v[34:37]
	ds_read_b128 v[236:239], v110 offset:64
	v_mfma_f32_16x16x32_bf16 v[34:37], v[248:251], v[56:59], v[34:37]
	ds_read_b128 v[220:223], v118 offset:19712
	v_mfma_f32_16x16x32_bf16 v[34:37], v[252:255], v[60:63], v[34:37]
	ds_read_b128 v[244:247], v118 offset:19776
	s_nop 7
	v_cvt_pk_bf16_f32 v34, v34, v35
	v_cvt_pk_bf16_f32 v35, v36, v37
	global_store_dwordx2 v[32:33], v[34:35], off offset:96
	ds_read_b128 v[36:39], v46 offset:35840
	ds_read_b128 v[32:35], v46 offset:35904
	v_pk_mul_f32 v[12:13], v[12:13], v[228:229]
	ds_read_b128 v[224:227], v110 offset:128
	v_pk_mul_f32 v[14:15], v[14:15], v[230:231]
	s_waitcnt lgkmcnt(2)
	s_nop 0
	v_mfma_f32_16x16x32_bf16 v[12:15], v[232:235], v[36:39], v[12:15]
	ds_read_b128 v[248:251], v118 offset:22016
	s_waitcnt lgkmcnt(2)
	v_mfma_f32_16x16x32_bf16 v[12:15], v[216:219], v[32:35], v[12:15]
	ds_read_b128 v[252:255], v118 offset:22080
	v_pk_mul_f32 v[0:1], v[0:1], v[236:237]
	ds_read_b128 v[228:231], v110 offset:192
	v_pk_mul_f32 v[2:3], v[2:3], v[238:239]
	s_nop 1
	v_mfma_f32_16x16x32_bf16 v[0:3], v[220:223], v[36:39], v[0:3]
	ds_read_b128 v[232:235], v118 offset:24320
	v_mfma_f32_16x16x32_bf16 v[0:3], v[244:247], v[32:35], v[0:3]
	ds_read_b128 v[216:219], v118 offset:24384
	s_waitcnt lgkmcnt(5)
	v_pk_mul_f32 v[8:9], v[8:9], v[224:225]
	ds_read_b128 v[236:239], v110 offset:256
	v_pk_mul_f32 v[10:11], v[10:11], v[226:227]
	s_waitcnt lgkmcnt(5)
	s_nop 0
	v_mfma_f32_16x16x32_bf16 v[8:11], v[248:251], v[36:39], v[8:11]
	ds_read_b128 v[220:223], v118 offset:26624
	s_waitcnt lgkmcnt(5)
	v_mfma_f32_16x16x32_bf16 v[8:11], v[252:255], v[32:35], v[8:11]
	ds_read_b128 v[244:247], v118 offset:26688
	s_waitcnt lgkmcnt(5)
	v_pk_mul_f32 v[4:5], v[4:5], v[228:229]
	ds_read_b128 v[224:227], v110 offset:320
	v_pk_mul_f32 v[6:7], v[6:7], v[230:231]
	s_waitcnt lgkmcnt(5)
	s_nop 0
	v_mfma_f32_16x16x32_bf16 v[4:7], v[232:235], v[36:39], v[4:7]
	ds_read_b128 v[248:251], v118 offset:28928
	s_waitcnt lgkmcnt(5)
	v_mfma_f32_16x16x32_bf16 v[4:7], v[216:219], v[32:35], v[4:7]
	ds_read_b128 v[252:255], v118 offset:28992
	s_waitcnt lgkmcnt(5)
	v_pk_mul_f32 v[20:21], v[20:21], v[236:237]
	ds_read_b128 v[228:231], v110 offset:384
	v_pk_mul_f32 v[22:23], v[22:23], v[238:239]
	s_waitcnt lgkmcnt(5)
	s_nop 0
	v_mfma_f32_16x16x32_bf16 v[20:23], v[220:223], v[36:39], v[20:23]
	ds_read_b128 v[232:235], v118 offset:31232
	s_waitcnt lgkmcnt(5)
	v_mfma_f32_16x16x32_bf16 v[20:23], v[244:247], v[32:35], v[20:23]
	ds_read_b128 v[216:219], v118 offset:31296
	s_waitcnt lgkmcnt(5)
	v_pk_mul_f32 v[16:17], v[16:17], v[224:225]
	ds_read_b128 v[236:239], v110 offset:448
	v_pk_mul_f32 v[18:19], v[18:19], v[226:227]
	s_waitcnt lgkmcnt(5)
	s_nop 0
	v_mfma_f32_16x16x32_bf16 v[16:19], v[248:251], v[36:39], v[16:19]
	s_waitcnt lgkmcnt(4)
	v_mfma_f32_16x16x32_bf16 v[16:19], v[252:255], v[32:35], v[16:19]
	s_waitcnt lgkmcnt(3)
	v_pk_mul_f32 v[24:25], v[24:25], v[228:229]
	v_pk_mul_f32 v[26:27], v[26:27], v[230:231]
	s_waitcnt lgkmcnt(2)
	s_nop 0
	v_mfma_f32_16x16x32_bf16 v[24:27], v[232:235], v[36:39], v[24:27]
	s_waitcnt lgkmcnt(1)
	v_mfma_f32_16x16x32_bf16 v[24:27], v[216:219], v[32:35], v[24:27]
	s_waitcnt lgkmcnt(0)
	v_pk_mul_f32 v[28:29], v[28:29], v[236:237]
	v_pk_mul_f32 v[30:31], v[30:31], v[238:239]
	ds_read_b128 v[40:43], v118 offset:33536
	s_waitcnt lgkmcnt(0)
	v_mfma_f32_16x16x32_bf16 v[28:31], v[40:43], v[36:39], v[28:31]
	ds_read_b128 v[36:39], v118 offset:33600
	s_waitcnt lgkmcnt(0)
	s_barrier
	v_mfma_f32_16x16x32_bf16 v[28:31], v[36:39], v[32:35], v[28:31]
	s_andn2_b64 exec, exec, s[58:59]
	s_cbranch_execz .LBB0_1481

.LBB0_1493:
	s_or_b64 exec, exec, s[54:55]
	v_sub_f32_e32 v34, v56, v35
	v_exp_f32_e32 v98, v34
	v_sub_f32_e32 v34, v77, v39
	v_exp_f32_e32 v56, v34
	v_mov_b32_e32 v34, v44
	v_mov_b32_e32 v35, v40
	v_mov_b32_e32 v40, v45
	s_waitcnt lgkmcnt(0)
	s_barrier
	s_waitcnt lgkmcnt(0)
	ds_read_b128 v[216:219], v114
	v_add_u32_e32 v197, v115, v117
	v_pk_mul_f32 v[34:35], v[98:99], v[34:35] op_sel_hi:[0,1]
	v_pk_mul_f32 v[40:41], v[56:57], v[40:41] op_sel_hi:[0,1]
	v_cvt_pk_bf16_f32 v39, v34, v35
	s_waitcnt lgkmcnt(0)
	v_pk_mul_f32 v[44:45], v[0:1], v[216:217]
	v_pk_mul_f32 v[46:47], v[2:3], v[218:219]
	v_cvt_pk_bf16_f32 v44, v44, v45
	v_cvt_pk_bf16_f32 v45, v46, v47
	ds_write_b64 v197, v[44:45] offset:45056
	ds_read_b128 v[220:223], v114 offset:64
	v_cvt_pk_bf16_f32 v35, v40, v41
	v_mov_b32_e32 v41, v32
	v_mov_b32_e32 v32, v43
	v_pk_mul_f32 v[32:33], v[56:57], v[32:33] op_sel_hi:[0,1]
	v_cvt_pk_bf16_f32 v34, v32, v33
	s_waitcnt lgkmcnt(0)
	v_pk_mul_f32 v[32:33], v[4:5], v[220:221]
	v_pk_mul_f32 v[48:49], v[6:7], v[222:223]
	v_cvt_pk_bf16_f32 v32, v32, v33
	v_cvt_pk_bf16_f32 v33, v48, v49
	ds_write_b64 v143, v[32:33] offset:45056
	ds_read_b128 v[224:227], v114 offset:128
	v_mov_b32_e32 v40, v42
	v_pk_mul_f32 v[54:55], v[98:99], v[40:41] op_sel_hi:[0,1]
	v_cvt_pk_bf16_f32 v38, v54, v55
	v_mov_b32_e32 v32, v52
	s_waitcnt lgkmcnt(0)
	v_pk_mul_f32 v[54:55], v[12:13], v[224:225]
	v_pk_mul_f32 v[198:199], v[14:15], v[226:227]
	v_cvt_pk_bf16_f32 v54, v54, v55
	v_cvt_pk_bf16_f32 v55, v198, v199
	ds_write_b64 v144, v[54:55] offset:45056
	ds_read_b128 v[228:231], v114 offset:192
	v_mov_b32_e32 v33, v36
	v_pk_mul_f32 v[32:33], v[98:99], v[32:33] op_sel_hi:[0,1]
	v_mov_b32_e32 v36, v53
	v_pk_mul_f32 v[202:203], v[56:57], v[36:37] op_sel_hi:[0,1]
	v_cvt_pk_bf16_f32 v37, v32, v33
	s_waitcnt lgkmcnt(0)
	v_pk_mul_f32 v[32:33], v[8:9], v[228:229]
	v_pk_mul_f32 v[198:199], v[10:11], v[230:231]
	v_cvt_pk_bf16_f32 v32, v32, v33
	v_cvt_pk_bf16_f32 v33, v198, v199
	ds_write_b64 v145, v[32:33] offset:45056
	ds_read_b128 v[232:235], v114 offset:256
	v_cvt_pk_bf16_f32 v33, v202, v203
	v_mov_b32_e32 v203, v78
	v_mov_b32_e32 v78, v81
	v_pk_mul_f32 v[78:79], v[56:57], v[78:79] op_sel_hi:[0,1]
	s_waitcnt lgkmcnt(0)
	v_pk_mul_f32 v[198:199], v[20:21], v[232:233]
	v_pk_mul_f32 v[200:201], v[22:23], v[234:235]
	v_cvt_pk_bf16_f32 v198, v198, v199
	v_cvt_pk_bf16_f32 v199, v200, v201
	ds_write_b64 v197, v[198:199] offset:45184
	ds_read_b128 v[236:239], v114 offset:320
	v_mov_b32_e32 v202, v80
	v_cvt_pk_bf16_f32 v32, v78, v79
	v_add_u32_e32 v77, v115, v113
	v_pk_mul_f32 v[202:203], v[98:99], v[202:203] op_sel_hi:[0,1]
	s_waitcnt lgkmcnt(0)
	v_pk_mul_f32 v[78:79], v[16:17], v[236:237]
	v_pk_mul_f32 v[80:81], v[18:19], v[238:239]
	v_cvt_pk_bf16_f32 v78, v78, v79
	v_cvt_pk_bf16_f32 v79, v80, v81
	ds_write_b64 v197, v[78:79] offset:45216
	ds_read_b128 v[244:247], v114 offset:384
	ds_read_b128 v[40:43], v77
	ds_read_b128 v[44:47], v77 offset:64
	v_cvt_pk_bf16_f32 v36, v202, v203
	v_mov_b32_e32 v199, v82
	s_waitcnt lgkmcnt(2)
	v_pk_mul_f32 v[78:79], v[28:29], v[244:245]
	v_pk_mul_f32 v[80:81], v[30:31], v[246:247]
	v_cvt_pk_bf16_f32 v78, v78, v79
	v_cvt_pk_bf16_f32 v79, v80, v81
	ds_write_b64 v197, v[78:79] offset:45248
	ds_read_b128 v[248:251], v114 offset:448
	v_mov_b32_e32 v82, v85
	v_mov_b32_e32 v198, v84
	v_pk_mul_f32 v[84:85], v[56:57], v[82:83] op_sel_hi:[0,1]
	v_cvt_pk_bf16_f32 v201, v84, v85
	s_waitcnt lgkmcnt(0)
	v_pk_mul_f32 v[78:79], v[24:25], v[248:249]
	v_pk_mul_f32 v[80:81], v[26:27], v[250:251]
	v_cvt_pk_bf16_f32 v78, v78, v79
	v_cvt_pk_bf16_f32 v79, v80, v81
	ds_write_b64 v197, v[78:79] offset:45280
	ds_read_b128 v[252:255], v146 offset:17408
	ds_read_b128 v[216:219], v146 offset:17472
	ds_read_b128 v[220:223], v146 offset:17536
	ds_read_b128 v[224:227], v146 offset:17600
	ds_read_b128 v[228:231], v146 offset:21760
	ds_read_b128 v[232:235], v146 offset:21824
	v_mov_b32_e32 v84, v88
	v_mov_b32_e32 v85, v86
	v_mov_b32_e32 v86, v89
	v_pk_mul_f32 v[84:85], v[98:99], v[84:85] op_sel_hi:[0,1]
	v_pk_mul_f32 v[86:87], v[56:57], v[86:87] op_sel_hi:[0,1]
	v_cvt_pk_bf16_f32 v82, v84, v85
	v_cvt_pk_bf16_f32 v200, v86, v87
	s_waitcnt lgkmcnt(5)
	v_mfma_f32_16x16x32_bf16 v[78:81], v[252:255], v[40:43], 0
	ds_read_b128 v[236:239], v146 offset:21888
	ds_read_b128 v[48:51], v77 offset:128
	ds_read_b128 v[52:55], v77 offset:192
	v_mov_b32_e32 v88, v92
	s_waitcnt lgkmcnt(7)
	v_mfma_f32_16x16x32_bf16 v[78:81], v[216:219], v[44:47], v[78:81]
	ds_read_b128 v[244:247], v146 offset:26112
	v_mov_b32_e32 v89, v90
	v_pk_mul_f32 v[88:89], v[98:99], v[88:89] op_sel_hi:[0,1]
	v_mov_b32_e32 v90, v93
	s_waitcnt lgkmcnt(2)
	v_mfma_f32_16x16x32_bf16 v[84:87], v[220:223], v[48:51], v[78:81]
	ds_read_b128 v[248:251], v146 offset:26176
	v_mul_f32_e64 v198, v98, v198
	v_mul_f32_e64 v199, v98, v199
	v_cvt_pk_bf16_f32 v83, v198, v199
	ds_read_b128 v[210:213], v146 offset:21952
	v_pk_mul_f32 v[78:79], v[56:57], v[90:91] op_sel_hi:[0,1]
	v_cvt_pk_bf16_f32 v81, v88, v89
	s_waitcnt lgkmcnt(3)
	v_mfma_f32_16x16x32_bf16 v[84:87], v[224:227], v[52:55], v[84:87]
	ds_read_b128 v[252:255], v146 offset:26240
	v_cvt_pk_bf16_f32 v199, v78, v79
	v_mov_b32_e32 v79, v94
	v_mov_b32_e32 v94, v97
	v_mov_b32_e32 v78, v96
	v_mfma_f32_16x16x32_bf16 v[202:205], v[228:231], v[40:43], 0
	ds_read_b128 v[216:219], v146 offset:26304
	v_mul_f32_e64 v96, v56, v94
	v_mul_f32_e64 v97, v56, v95
	v_pk_mul_f32 v[78:79], v[98:99], v[78:79] op_sel_hi:[0,1]
	v_mfma_f32_16x16x32_bf16 v[88:91], v[232:235], v[44:47], v[202:205]
	ds_read_b128 v[220:223], v146 offset:30464
	v_cvt_pk_bf16_f32 v80, v78, v79
	v_cvt_pk_bf16_f32 v198, v96, v97
	v_cndmask_b32_e64 v56, v84, 0, s[4:5]
	v_mfma_f32_16x16x32_bf16 v[88:91], v[236:239], v[48:51], v[88:91]
	ds_read_b128 v[224:227], v146 offset:30592
	v_cndmask_b32_e64 v77, v85, 0, s[10:11]
	v_cndmask_b32_e64 v79, v86, 0, s[12:13]
	s_waitcnt lgkmcnt(6)
	v_mfma_f32_16x16x32_bf16 v[92:95], v[244:247], v[40:43], 0
	v_cndmask_b32_e64 v96, v87, 0, s[14:15]
	v_cvt_pk_bf16_f32 v78, v56, v77
	s_waitcnt lgkmcnt(5)
	v_mfma_f32_16x16x32_bf16 v[92:95], v[248:251], v[44:47], v[92:95]
	v_cvt_pk_bf16_f32 v79, v79, v96
	v_add_u32_e32 v74, -1, v74
	s_waitcnt lgkmcnt(4)
	v_mfma_f32_16x16x32_bf16 v[88:91], v[210:213], v[52:55], v[88:91]
	s_add_i32 s66, s66, 1
	s_waitcnt lgkmcnt(3)
	v_mfma_f32_16x16x32_bf16 v[92:95], v[252:255], v[48:51], v[92:95]
	ds_read_b128 v[206:209], v146 offset:30528
	s_nop 4
	v_cndmask_b32_e64 v56, v88, 0, s[16:17]
	v_cndmask_b32_e64 v77, v89, 0, s[18:19]
	v_cndmask_b32_e64 v97, v90, 0, s[20:21]
	v_cndmask_b32_e64 v98, v91, 0, s[22:23]
	s_waitcnt lgkmcnt(3)
	v_mfma_f32_16x16x32_bf16 v[84:87], v[216:219], v[52:55], v[92:95]
	v_cvt_pk_bf16_f32 v96, v56, v77
	v_cvt_pk_bf16_f32 v97, v97, v98
	s_waitcnt lgkmcnt(2)
	v_mfma_f32_16x16x32_bf16 v[92:95], v[220:223], v[40:43], 0
	ds_read_b128 v[202:205], v146 offset:30656
	s_nop 2
	v_cndmask_b32_e64 v56, v84, 0, s[24:25]
	v_cndmask_b32_e64 v77, v85, 0, s[26:27]
	s_waitcnt lgkmcnt(1)
	v_mfma_f32_16x16x32_bf16 v[92:95], v[206:209], v[44:47], v[92:95]
	v_cndmask_b32_e64 v84, v86, 0, s[28:29]
	v_cndmask_b32_e64 v85, v87, 0, s[30:31]
	v_mfma_f32_16x16x32_bf16 v[88:91], v[224:227], v[48:51], v[92:95]
	s_barrier
	s_nop 2
	s_nop 0
	v_cvt_pk_bf16_f32 v93, v84, v85
	v_mfma_f32_16x16x32_bf16 v[84:87], v[202:205], v[52:55], v[88:91]
	v_cvt_pk_bf16_f32 v92, v56, v77
	s_nop 6
	v_cndmask_b32_e64 v56, v84, 0, s[34:35]
	v_cndmask_b32_e64 v77, v85, 0, s[36:37]
	v_cvt_pk_bf16_f32 v84, v56, v77
	v_add_u32_e32 v56, v116, v117
	v_cndmask_b32_e64 v85, v86, 0, s[38:39]
	v_cndmask_b32_e64 v86, v87, 0, s[40:41]
	v_add_u32_e32 v56, 0xf000, v56
	v_cvt_pk_bf16_f32 v85, v85, v86
	ds_write2_b64 v56, v[78:79], v[96:97] offset0:128 offset1:132
	ds_write2_b64 v56, v[92:93], v[84:85] offset0:136 offset1:140
	v_add_u32_e32 v56, v118, v119
	ds_write_b128 v56, v[80:83] offset:17408
	ds_write_b128 v56, v[36:39] offset:17424
	ds_write_b128 v56, v[198:201] offset:17552
	ds_write_b128 v56, v[32:35] offset:17568
	s_waitcnt lgkmcnt(0)
	s_barrier
	s_waitcnt lgkmcnt(0)
	ds_read_b128 v[216:219], v147 offset:35840
	ds_read_b128 v[220:223], v147 offset:35904
	ds_read_b128 v[224:227], v146 offset:45056
	ds_read_b128 v[228:231], v146 offset:49408
	ds_read_b128 v[232:235], v146 offset:53760
	ds_read_b128 v[236:239], v146 offset:45120
	v_add_u32_e32 v77, v116, v113
	ds_read_b128 v[78:81], v77 offset:62464
	ds_read_b128 v[82:85], v77 offset:62528
	s_waitcnt lgkmcnt(1)
	v_mfma_f32_16x16x32_bf16 v[32:35], v[216:219], v[78:81], 0
	ds_read_b128 v[244:247], v146 offset:45184
	s_waitcnt lgkmcnt(1)
	v_mfma_f32_16x16x32_bf16 v[32:35], v[220:223], v[82:85], v[32:35]
	ds_read_b128 v[248:251], v146 offset:45248
	v_ashrrev_i32_e32 v56, 9, v65
	v_cmp_gt_i32_e32 vcc, 32, v56
	v_mfma_f32_16x16x32_bf16 v[32:35], v[224:227], v[40:43], v[32:35]
	ds_read_b128 v[252:255], v147 offset:38144
	v_subrev_u32_e32 v65, 64, v65
	v_mfma_f32_16x16x32_bf16 v[32:35], v[236:239], v[44:47], v[32:35]
	ds_read_b128 v[216:219], v147 offset:38208
	s_waitcnt lgkmcnt(3)
	v_mfma_f32_16x16x32_bf16 v[32:35], v[244:247], v[48:51], v[32:35]
	ds_read_b128 v[220:223], v146 offset:49472
	s_waitcnt lgkmcnt(3)
	v_mfma_f32_16x16x32_bf16 v[32:35], v[248:251], v[52:55], v[32:35]
	ds_read_b128 v[224:227], v146 offset:49536
	s_waitcnt lgkmcnt(3)
	v_mfma_f32_16x16x32_bf16 v[86:89], v[252:255], v[78:81], 0
	ds_read_b128 v[236:239], v146 offset:49600
	s_waitcnt lgkmcnt(3)
	v_mfma_f32_16x16x32_bf16 v[36:39], v[216:219], v[82:85], v[86:89]
	ds_read_b128 v[244:247], v147 offset:40448
	s_nop 6
	v_mfma_f32_16x16x32_bf16 v[36:39], v[228:231], v[40:43], v[36:39]
	ds_read_b128 v[248:251], v147 offset:40512
	s_waitcnt lgkmcnt(4)
	v_mfma_f32_16x16x32_bf16 v[36:39], v[220:223], v[44:47], v[36:39]
	ds_read_b128 v[252:255], v146 offset:53824
	s_waitcnt lgkmcnt(4)
	v_mfma_f32_16x16x32_bf16 v[36:39], v[224:227], v[48:51], v[36:39]
	ds_read_b128 v[216:219], v146 offset:53888
	s_waitcnt lgkmcnt(4)
	v_mfma_f32_16x16x32_bf16 v[36:39], v[236:239], v[52:55], v[36:39]
	ds_read_b128 v[228:231], v146 offset:53952
	s_waitcnt lgkmcnt(4)
	v_mfma_f32_16x16x32_bf16 v[90:93], v[244:247], v[78:81], 0
	ds_read_b128 v[220:223], v147 offset:42752
	s_waitcnt lgkmcnt(4)
	v_mfma_f32_16x16x32_bf16 v[86:89], v[248:251], v[82:85], v[90:93]
	ds_read_b128 v[224:227], v147 offset:42816
	s_nop 5
	v_mfma_f32_16x16x32_bf16 v[86:89], v[232:235], v[40:43], v[86:89]
	ds_read_b128 v[236:239], v146 offset:58176
	s_waitcnt lgkmcnt(5)
	v_mfma_f32_16x16x32_bf16 v[86:89], v[252:255], v[44:47], v[86:89]
	ds_read_b128 v[244:247], v146 offset:58304
	s_waitcnt lgkmcnt(5)
	v_mfma_f32_16x16x32_bf16 v[86:89], v[216:219], v[48:51], v[86:89]
	ds_read_b128 v[248:251], v146 offset:58240
	s_waitcnt lgkmcnt(5)
	v_mfma_f32_16x16x32_bf16 v[86:89], v[228:231], v[52:55], v[86:89]
	ds_read_b128 v[232:235], v147 offset:17408
	ds_read_b128 v[198:201], v146 offset:58112
	s_waitcnt lgkmcnt(6)
	v_mfma_f32_16x16x32_bf16 v[78:81], v[220:223], v[78:81], 0
	ds_read_b128 v[252:255], v120
	v_lshlrev_b32_e32 v94, 1, v56
	v_subrev_u32_e32 v96, 63, v94
	v_cndmask_b32_e32 v56, v148, v149, vcc
	s_waitcnt lgkmcnt(6)
	v_mfma_f32_16x16x32_bf16 v[78:81], v[224:227], v[82:85], v[78:81]
	ds_read_b128 v[216:219], v147 offset:17472
	v_or_b32_e32 v90, 1, v94
	v_ashrrev_i32_e32 v91, 31, v90
	s_waitcnt lgkmcnt(2)
	v_mfma_f32_16x16x32_bf16 v[40:43], v[198:201], v[40:43], v[78:81]
	v_cndmask_b32_e32 v95, 0, v91, vcc
	v_cndmask_b32_e32 v94, v96, v90, vcc
	s_nop 0
	v_mfma_f32_16x16x32_bf16 v[40:43], v[236:239], v[44:47], v[40:43]
	ds_read_b128 v[228:231], v120 offset:64
	v_lshl_add_u64 v[44:45], s[94:95], 0, v[56:57]
	v_lshlrev_b64 v[46:47], 20, v[94:95]
	v_lshl_add_u64 v[94:95], v[44:45], 0, v[46:47]
	v_mfma_f32_16x16x32_bf16 v[40:43], v[248:251], v[48:51], v[40:43]
	ds_read_b128 v[220:223], v147 offset:19712
	v_and_b32_e32 v44, 0x7fc00, v164
	v_lshlrev_b32_e32 v56, 1, v44
	v_cvt_pk_bf16_f32 v96, v32, v33
	v_mfma_f32_16x16x32_bf16 v[40:43], v[244:247], v[52:55], v[40:43]
	ds_read_b128 v[224:227], v147 offset:19776
	ds_read_b128 v[52:55], v77 offset:35840
	ds_read_b128 v[78:81], v77 offset:35904
	s_waitcnt lgkmcnt(6)
	v_pk_mul_f32 v[0:1], v[0:1], v[252:253]
	ds_read_b128 v[236:239], v147 offset:22016
	v_pk_mul_f32 v[2:3], v[2:3], v[254:255]
	v_cvt_pk_bf16_f32 v97, v34, v35
	s_waitcnt lgkmcnt(2)
	v_mfma_f32_16x16x32_bf16 v[0:3], v[232:235], v[52:55], v[0:3]
	ds_read_b128 v[248:251], v120 offset:128
	v_pk_mul_f32 v[4:5], v[4:5], v[228:229]
	ds_read_b128 v[244:247], v147 offset:22080
	v_pk_mul_f32 v[6:7], v[6:7], v[230:231]
	s_waitcnt lgkmcnt(3)
	v_mfma_f32_16x16x32_bf16 v[0:3], v[216:219], v[78:81], v[0:3]
	ds_read_b128 v[252:255], v147 offset:24320
	v_lshl_add_u64 v[94:95], v[94:95], 0, v[56:57]
	v_mov_b32_e32 v77, v57
	v_lshl_add_u64 v[94:95], v[94:95], 0, v[76:77]
	v_mfma_f32_16x16x32_bf16 v[4:7], v[220:223], v[52:55], v[4:7]
	ds_read_b128 v[232:235], v147 offset:24384
	v_lshl_add_u64 v[94:95], v[58:59], 1, v[94:95]
	v_lshlrev_b32_e32 v56, 1, v112
	v_mfma_f32_16x16x32_bf16 v[4:7], v[224:227], v[78:81], v[4:7]
	ds_read_b128 v[228:231], v147 offset:26624
	ds_read_b128 v[90:93], v120 offset:192
	s_waitcnt lgkmcnt(5)
	v_pk_mul_f32 v[12:13], v[12:13], v[248:249]
	ds_read_b128 v[216:219], v120 offset:256
	v_pk_mul_f32 v[14:15], v[14:15], v[250:251]
	v_lshl_add_u64 v[94:95], v[94:95], 0, v[56:57]
	s_nop 0
	v_mfma_f32_16x16x32_bf16 v[12:15], v[236:239], v[52:55], v[12:15]
	ds_read_b128 v[220:223], v147 offset:26688
	s_waitcnt lgkmcnt(2)
	v_pk_mul_f32 v[8:9], v[8:9], v[90:91]
	v_pk_mul_f32 v[10:11], v[10:11], v[92:93]
	v_mfma_f32_16x16x32_bf16 v[12:15], v[244:247], v[78:81], v[12:15]
	ds_read_b128 v[224:227], v120 offset:320
	v_cvt_pk_bf16_f32 v90, v36, v37
	v_cvt_pk_bf16_f32 v91, v38, v39
	v_cmp_eq_u32_e32 vcc, -2, v74
	v_mfma_f32_16x16x32_bf16 v[8:11], v[252:255], v[52:55], v[8:11]
	ds_read_b128 v[248:251], v147 offset:28992
	v_add_u32_e32 v164, 0xffff0000, v164
	s_or_b64 s[52:53], vcc, s[52:53]
	v_mfma_f32_16x16x32_bf16 v[8:11], v[232:235], v[78:81], v[8:11]
	ds_read_b128 v[236:239], v147 offset:31232
	s_waitcnt lgkmcnt(4)
	v_pk_mul_f32 v[20:21], v[20:21], v[216:217]
	ds_read_b128 v[244:247], v120 offset:384
	v_pk_mul_f32 v[22:23], v[22:23], v[218:219]
	ds_read_b128 v[82:85], v147 offset:28928
	global_store_dwordx2 v[94:95], v[96:97], off
	v_mfma_f32_16x16x32_bf16 v[20:23], v[228:231], v[52:55], v[20:23]
	s_waitcnt lgkmcnt(4)
	v_pk_mul_f32 v[16:17], v[16:17], v[224:225]
	v_pk_mul_f32 v[18:19], v[18:19], v[226:227]
	v_mfma_f32_16x16x32_bf16 v[20:23], v[220:223], v[78:81], v[20:23]
	global_store_dwordx2 v[94:95], v[90:91], off offset:32
	s_waitcnt lgkmcnt(1)
	v_pk_mul_f32 v[28:29], v[28:29], v[244:245]
	s_waitcnt lgkmcnt(0)
	v_mfma_f32_16x16x32_bf16 v[16:19], v[82:85], v[52:55], v[16:19]
	v_mul_f32_e64 v30, v30, v246
	v_mul_f32_e64 v31, v31, v247
	v_cvt_pk_bf16_f32 v82, v86, v87
	v_cvt_pk_bf16_f32 v83, v88, v89
	v_mfma_f32_16x16x32_bf16 v[16:19], v[248:251], v[78:81], v[16:19]
	ds_read_b128 v[44:47], v147 offset:31296
	ds_read_b128 v[48:51], v120 offset:448
	ds_read_b128 v[36:39], v147 offset:33536
	global_store_dwordx2 v[94:95], v[82:83], off offset:64
	v_mfma_f32_16x16x32_bf16 v[28:31], v[236:239], v[52:55], v[28:31]
	ds_read_b128 v[32:35], v147 offset:33600
	s_waitcnt lgkmcnt(2)
	v_pk_mul_f32 v[24:25], v[24:25], v[48:49]
	v_pk_mul_f32 v[26:27], v[26:27], v[50:51]
	v_mfma_f32_16x16x32_bf16 v[28:31], v[44:47], v[78:81], v[28:31]
	s_nop 0
	s_waitcnt lgkmcnt(1)
	v_mfma_f32_16x16x32_bf16 v[24:27], v[36:39], v[52:55], v[24:27]
	v_cvt_pk_bf16_f32 v36, v40, v41
	v_cvt_pk_bf16_f32 v37, v42, v43
	global_store_dwordx2 v[94:95], v[36:37], off offset:96
	s_waitcnt lgkmcnt(0)
	v_mfma_f32_16x16x32_bf16 v[24:27], v[32:35], v[78:81], v[24:27]
	s_barrier
	s_andn2_b64 exec, exec, s[52:53]
	s_cbranch_execz .LBB0_1498

.LBB0_1506:
	s_or_b64 exec, exec, s[58:59]
	v_sub_f32_e32 v32, v156, v33
	v_exp_f32_e32 v156, v32
	v_sub_f32_e32 v32, v157, v35
	v_exp_f32_e32 v158, v32
	v_mov_b32_e32 v32, v36
	v_mov_b32_e32 v33, v38
	v_mov_b32_e32 v38, v37
	v_pk_mul_f32 v[32:33], v[156:157], v[32:33] op_sel_hi:[0,1]
	v_pk_mul_f32 v[34:35], v[158:159], v[38:39] op_sel_hi:[0,1]
	v_cvt_pk_bf16_f32 v36, v32, v33
	v_cvt_pk_bf16_f32 v32, v34, v35
	v_mov_b32_e32 v34, v40
	v_mov_b32_e32 v35, v42
	v_pk_mul_f32 v[34:35], v[156:157], v[34:35] op_sel_hi:[0,1]
	v_mov_b32_e32 v42, v41
	v_cvt_pk_bf16_f32 v37, v34, v35
	v_mov_b32_e32 v34, v44
	v_mov_b32_e32 v35, v46
	v_mov_b32_e32 v46, v45
	v_pk_mul_f32 v[38:39], v[158:159], v[42:43] op_sel_hi:[0,1]
	v_pk_mul_f32 v[34:35], v[156:157], v[34:35] op_sel_hi:[0,1]
	v_pk_mul_f32 v[40:41], v[158:159], v[46:47] op_sel_hi:[0,1]
	v_cvt_pk_bf16_f32 v33, v38, v39
	v_cvt_pk_bf16_f32 v38, v34, v35
	v_cvt_pk_bf16_f32 v34, v40, v41
	v_mov_b32_e32 v40, v48
	v_mov_b32_e32 v41, v50
	v_pk_mul_f32 v[40:41], v[156:157], v[40:41] op_sel_hi:[0,1]
	v_mov_b32_e32 v50, v49
	v_pk_mul_f32 v[42:43], v[158:159], v[50:51] op_sel_hi:[0,1]
	v_cvt_pk_bf16_f32 v39, v40, v41
	v_mov_b32_e32 v40, v52
	v_mov_b32_e32 v41, v54
	v_mov_b32_e32 v54, v53
	v_cvt_pk_bf16_f32 v35, v42, v43
	v_pk_mul_f32 v[40:41], v[156:157], v[40:41] op_sel_hi:[0,1]
	v_pk_mul_f32 v[42:43], v[158:159], v[54:55] op_sel_hi:[0,1]
	v_cvt_pk_bf16_f32 v44, v40, v41
	v_cvt_pk_bf16_f32 v40, v42, v43
	v_mov_b32_e32 v42, v56
	v_mov_b32_e32 v43, v60
	v_pk_mul_f32 v[42:43], v[156:157], v[42:43] op_sel_hi:[0,1]
	v_mov_b32_e32 v60, v57
	v_cvt_pk_bf16_f32 v45, v42, v43
	v_mov_b32_e32 v42, v86
	v_mov_b32_e32 v43, v88
	v_mov_b32_e32 v88, v87
	v_pk_mul_f32 v[46:47], v[158:159], v[60:61] op_sel_hi:[0,1]
	v_pk_mul_f32 v[42:43], v[156:157], v[42:43] op_sel_hi:[0,1]
	v_pk_mul_f32 v[48:49], v[158:159], v[88:89] op_sel_hi:[0,1]
	v_cvt_pk_bf16_f32 v41, v46, v47
	v_cvt_pk_bf16_f32 v46, v42, v43
	v_cvt_pk_bf16_f32 v42, v48, v49
	v_mov_b32_e32 v48, v62
	v_mov_b32_e32 v49, v58
	v_mov_b32_e32 v58, v63
	v_pk_mul_f32 v[48:49], v[156:157], v[48:49] op_sel_hi:[0,1]
	v_pk_mul_f32 v[50:51], v[158:159], v[58:59] op_sel_hi:[0,1]
	v_cvt_pk_bf16_f32 v47, v48, v49
	v_cvt_pk_bf16_f32 v43, v50, v51
	s_waitcnt lgkmcnt(0)
	s_barrier
	s_waitcnt lgkmcnt(0)
	ds_read_b128 v[216:219], v114
	v_add_u32_e32 v52, v115, v117
	v_add_u32_e32 v60, v115, v113
	v_cmp_eq_u32_e32 vcc, s74, v133
	v_lshl_add_u64 v[80:81], v[80:81], 0, s[54:55]
	s_waitcnt lgkmcnt(0)
	v_pk_mul_f32 v[48:49], v[12:13], v[216:217]
	v_pk_mul_f32 v[50:51], v[14:15], v[218:219]
	v_cvt_pk_bf16_f32 v48, v48, v49
	v_cvt_pk_bf16_f32 v49, v50, v51
	ds_write_b64 v52, v[48:49] offset:45056
	ds_read_b128 v[220:223], v114 offset:64
	v_lshl_add_u64 v[82:83], v[82:83], 0, s[54:55]
	v_lshl_add_u64 v[84:85], v[84:85], 0, s[54:55]
	s_or_b64 s[56:57], vcc, s[56:57]
	s_waitcnt lgkmcnt(0)
	v_pk_mul_f32 v[48:49], v[0:1], v[220:221]
	v_pk_mul_f32 v[50:51], v[2:3], v[222:223]
	v_cvt_pk_bf16_f32 v48, v48, v49
	v_cvt_pk_bf16_f32 v49, v50, v51
	ds_write_b64 v91, v[48:49] offset:45056
	ds_read_b128 v[224:227], v114 offset:128
	s_waitcnt lgkmcnt(0)
	v_pk_mul_f32 v[48:49], v[8:9], v[224:225]
	v_pk_mul_f32 v[50:51], v[10:11], v[226:227]
	v_cvt_pk_bf16_f32 v48, v48, v49
	v_cvt_pk_bf16_f32 v49, v50, v51
	ds_write_b64 v92, v[48:49] offset:45056
	ds_read_b128 v[228:231], v114 offset:192
	s_waitcnt lgkmcnt(0)
	v_pk_mul_f32 v[48:49], v[4:5], v[228:229]
	v_pk_mul_f32 v[50:51], v[6:7], v[230:231]
	v_cvt_pk_bf16_f32 v48, v48, v49
	v_cvt_pk_bf16_f32 v49, v50, v51
	ds_write_b64 v93, v[48:49] offset:45056
	ds_read_b128 v[232:235], v114 offset:256
	s_waitcnt lgkmcnt(0)
	v_pk_mul_f32 v[48:49], v[20:21], v[232:233]
	v_pk_mul_f32 v[50:51], v[22:23], v[234:235]
	v_cvt_pk_bf16_f32 v48, v48, v49
	v_cvt_pk_bf16_f32 v49, v50, v51
	ds_write_b64 v52, v[48:49] offset:45184
	ds_read_b128 v[236:239], v114 offset:320
	s_waitcnt lgkmcnt(0)
	v_pk_mul_f32 v[48:49], v[16:17], v[236:237]
	v_pk_mul_f32 v[50:51], v[18:19], v[238:239]
	v_cvt_pk_bf16_f32 v48, v48, v49
	v_cvt_pk_bf16_f32 v49, v50, v51
	ds_write_b64 v52, v[48:49] offset:45216
	ds_read_b128 v[244:247], v114 offset:384
	s_waitcnt lgkmcnt(0)
	v_pk_mul_f32 v[48:49], v[24:25], v[244:245]
	v_pk_mul_f32 v[50:51], v[26:27], v[246:247]
	v_cvt_pk_bf16_f32 v48, v48, v49
	v_cvt_pk_bf16_f32 v49, v50, v51
	ds_write_b64 v52, v[48:49] offset:45248
	ds_read_b128 v[248:251], v114 offset:448
	s_waitcnt lgkmcnt(0)
	v_pk_mul_f32 v[48:49], v[28:29], v[248:249]
	v_pk_mul_f32 v[50:51], v[30:31], v[250:251]
	v_cvt_pk_bf16_f32 v48, v48, v49
	v_cvt_pk_bf16_f32 v49, v50, v51
	ds_write_b64 v52, v[48:49] offset:45280
	ds_read_b128 v[252:255], v94 offset:17408
	ds_read_b128 v[216:219], v94 offset:17472
	ds_read_b128 v[220:223], v94 offset:21824
	ds_read_b128 v[224:227], v94 offset:17536
	ds_read_b128 v[228:231], v94 offset:17600
	ds_read_b128 v[232:235], v94 offset:21760
	ds_read_b128 v[48:51], v60
	ds_read_b128 v[52:55], v60 offset:64
	ds_read_b128 v[56:59], v60 offset:128
	ds_read_b128 v[60:63], v60 offset:192
	s_waitcnt lgkmcnt(3)
	v_mfma_f32_16x16x32_bf16 v[86:89], v[252:255], v[48:51], 0
	ds_read_b128 v[236:239], v94 offset:21888
	s_waitcnt lgkmcnt(3)
	v_mfma_f32_16x16x32_bf16 v[86:89], v[216:219], v[52:55], v[86:89]
	ds_read_b128 v[244:247], v94 offset:21952
	s_waitcnt lgkmcnt(3)
	v_mfma_f32_16x16x32_bf16 v[86:89], v[224:227], v[56:59], v[86:89]
	ds_read_b128 v[248:251], v94 offset:26176
	s_waitcnt lgkmcnt(3)
	v_mfma_f32_16x16x32_bf16 v[86:89], v[228:231], v[60:63], v[86:89]
	ds_read_b128 v[252:255], v94 offset:26112
	s_nop 6
	v_cndmask_b32_e64 v86, v86, 0, s[6:7]
	v_mfma_f32_16x16x32_bf16 v[156:159], v[232:235], v[48:51], 0
	ds_read_b128 v[216:219], v94 offset:26240
	v_cndmask_b32_e64 v87, 0, v87, s[8:9]
	v_cndmask_b32_e64 v88, v88, 0, s[10:11]
	v_cndmask_b32_e64 v89, v89, 0, s[12:13]
	v_mfma_f32_16x16x32_bf16 v[156:159], v[220:223], v[52:55], v[156:159]
	ds_read_b128 v[224:227], v94 offset:26304
	v_cvt_pk_bf16_f32 v86, v86, v87
	v_cvt_pk_bf16_f32 v87, v88, v89
	s_waitcnt lgkmcnt(5)
	v_mfma_f32_16x16x32_bf16 v[156:159], v[236:239], v[56:59], v[156:159]
	ds_read_b128 v[228:231], v94 offset:30528
	s_waitcnt lgkmcnt(5)
	v_mfma_f32_16x16x32_bf16 v[156:159], v[244:247], v[60:63], v[156:159]
	ds_read_b128 v[232:235], v94 offset:30464
	s_nop 6
	v_cndmask_b32_e64 v88, v156, 0, s[14:15]
	v_cndmask_b32_e64 v89, v157, 0, s[16:17]
	v_cndmask_b32_e64 v156, v158, 0, s[18:19]
	v_cndmask_b32_e64 v157, v159, 0, s[20:21]
	v_cvt_pk_bf16_f32 v88, v88, v89
	v_cvt_pk_bf16_f32 v89, v156, v157
	s_waitcnt lgkmcnt(4)
	v_mfma_f32_16x16x32_bf16 v[156:159], v[252:255], v[48:51], 0
	ds_read_b128 v[220:223], v94 offset:30592
	v_mfma_f32_16x16x32_bf16 v[156:159], v[248:251], v[52:55], v[156:159]
	s_waitcnt lgkmcnt(4)
	v_mfma_f32_16x16x32_bf16 v[156:159], v[216:219], v[56:59], v[156:159]
	s_waitcnt lgkmcnt(3)
	v_mfma_f32_16x16x32_bf16 v[156:159], v[224:227], v[60:63], v[156:159]
	s_nop 6
	s_nop 0
	v_cndmask_b32_e64 v156, v156, 0, s[22:23]
	v_cndmask_b32_e64 v157, v157, 0, s[24:25]
	v_cndmask_b32_e64 v158, v158, 0, s[26:27]
	v_cndmask_b32_e64 v159, v159, 0, s[28:29]
	v_cvt_pk_bf16_f32 v164, v156, v157
	v_cvt_pk_bf16_f32 v165, v158, v159
	s_waitcnt lgkmcnt(1)
	v_mfma_f32_16x16x32_bf16 v[156:159], v[232:235], v[48:51], 0
	v_mfma_f32_16x16x32_bf16 v[156:159], v[228:231], v[52:55], v[156:159]
	s_waitcnt lgkmcnt(0)
	v_mfma_f32_16x16x32_bf16 v[156:159], v[220:223], v[56:59], v[156:159]
	ds_read_b128 v[160:163], v94 offset:30656
	s_waitcnt lgkmcnt(0)
	s_barrier
	v_mfma_f32_16x16x32_bf16 v[156:159], v[160:163], v[60:63], v[156:159]
	s_nop 7
	v_cndmask_b32_e64 v156, v156, 0, s[30:31]
	v_cndmask_b32_e64 v157, v157, 0, s[34:35]
	v_cndmask_b32_e64 v158, v158, 0, s[36:37]
	v_cndmask_b32_e64 v159, v159, 0, s[38:39]
	v_cvt_pk_bf16_f32 v156, v156, v157
	v_cvt_pk_bf16_f32 v157, v158, v159
	v_add_u32_e32 v158, v116, v117
	v_add_u32_e32 v158, 0xf000, v158
	ds_write2_b64 v158, v[86:87], v[88:89] offset0:128 offset1:132
	ds_write2_b64 v158, v[164:165], v[156:157] offset0:136 offset1:140
	v_add_u32_e32 v86, v118, v119
	ds_write_b128 v86, v[36:39] offset:17408
	ds_write_b128 v86, v[44:47] offset:17424
	ds_write_b128 v86, v[32:35] offset:17552
	ds_write_b128 v86, v[40:43] offset:17568
	v_add_u32_e32 v46, v116, v113
	s_waitcnt lgkmcnt(0)
	s_barrier
	s_waitcnt lgkmcnt(0)
	ds_read_b128 v[216:219], v46 offset:62464
	ds_read_b128 v[220:223], v46 offset:62528
	ds_read_b128 v[224:227], v95 offset:35840
	ds_read_b128 v[228:231], v95 offset:35904
	ds_read_b128 v[232:235], v94 offset:45056
	ds_read_b128 v[236:239], v94 offset:45120
	s_waitcnt lgkmcnt(3)
	v_mfma_f32_16x16x32_bf16 v[42:45], v[224:227], v[216:219], 0
	ds_read_b128 v[244:247], v94 offset:45184
	ds_read_b128 v[248:251], v94 offset:45248
	v_lshlrev_b64 v[32:33], 11, v[70:71]
	v_lshl_add_u64 v[32:33], v[78:79], 0, v[32:33]
	v_add_u32_e32 v70, 64, v70
	s_waitcnt lgkmcnt(4)
	v_mfma_f32_16x16x32_bf16 v[42:45], v[228:231], v[220:223], v[42:45]
	ds_read_b128 v[252:255], v95 offset:38208
	ds_read_b128 v[224:227], v95 offset:38144
	s_waitcnt lgkmcnt(5)
	v_mfma_f32_16x16x32_bf16 v[42:45], v[232:235], v[48:51], v[42:45]
	ds_read_b128 v[228:231], v94 offset:49408
	s_waitcnt lgkmcnt(5)
	v_mfma_f32_16x16x32_bf16 v[42:45], v[236:239], v[52:55], v[42:45]
	ds_read_b128 v[232:235], v94 offset:49472
	s_waitcnt lgkmcnt(5)
	v_mfma_f32_16x16x32_bf16 v[42:45], v[244:247], v[56:59], v[42:45]
	ds_read_b128 v[236:239], v94 offset:49536
	s_waitcnt lgkmcnt(5)
	v_mfma_f32_16x16x32_bf16 v[42:45], v[248:251], v[60:63], v[42:45]
	ds_read_b128 v[244:247], v94 offset:49600
	s_nop 6
	v_cvt_pk_bf16_f32 v42, v42, v43
	v_cvt_pk_bf16_f32 v43, v44, v45
	global_store_dwordx2 v[32:33], v[42:43], off
	s_waitcnt lgkmcnt(4)
	v_mfma_f32_16x16x32_bf16 v[42:45], v[224:227], v[216:219], 0
	ds_read_b128 v[248:251], v95 offset:40512
	v_mfma_f32_16x16x32_bf16 v[42:45], v[252:255], v[220:223], v[42:45]
	ds_read_b128 v[224:227], v95 offset:40448
	s_waitcnt lgkmcnt(5)
	v_mfma_f32_16x16x32_bf16 v[42:45], v[228:231], v[48:51], v[42:45]
	ds_read_b128 v[252:255], v94 offset:53760
	s_waitcnt lgkmcnt(5)
	v_mfma_f32_16x16x32_bf16 v[42:45], v[232:235], v[52:55], v[42:45]
	ds_read_b128 v[228:231], v94 offset:53824
	s_waitcnt lgkmcnt(5)
	v_mfma_f32_16x16x32_bf16 v[42:45], v[236:239], v[56:59], v[42:45]
	ds_read_b128 v[232:235], v94 offset:53888
	s_waitcnt lgkmcnt(5)
	v_mfma_f32_16x16x32_bf16 v[42:45], v[244:247], v[60:63], v[42:45]
	ds_read_b128 v[236:239], v95 offset:42752
	s_nop 6
	v_cvt_pk_bf16_f32 v42, v42, v43
	v_cvt_pk_bf16_f32 v43, v44, v45
	global_store_dwordx2 v[32:33], v[42:43], off offset:32
	s_waitcnt lgkmcnt(4)
	v_mfma_f32_16x16x32_bf16 v[42:45], v[224:227], v[216:219], 0
	ds_read_b128 v[244:247], v94 offset:58112
	v_mfma_f32_16x16x32_bf16 v[42:45], v[248:251], v[220:223], v[42:45]
	ds_read_b128 v[224:227], v94 offset:58176
	s_waitcnt lgkmcnt(5)
	v_mfma_f32_16x16x32_bf16 v[42:45], v[252:255], v[48:51], v[42:45]
	ds_read_b128 v[248:251], v94 offset:58240
	s_waitcnt lgkmcnt(5)
	v_mfma_f32_16x16x32_bf16 v[42:45], v[228:231], v[52:55], v[42:45]
	ds_read_b128 v[252:255], v94 offset:58304
	s_waitcnt lgkmcnt(5)
	v_mfma_f32_16x16x32_bf16 v[42:45], v[232:235], v[56:59], v[42:45]
	ds_read_b128 v[228:231], v120
	ds_read_b128 v[86:89], v94 offset:53952
	s_waitcnt lgkmcnt(0)
	v_mfma_f32_16x16x32_bf16 v[42:45], v[86:89], v[60:63], v[42:45]
	s_nop 7
	v_cvt_pk_bf16_f32 v42, v42, v43
	v_cvt_pk_bf16_f32 v43, v44, v45
	global_store_dwordx2 v[32:33], v[42:43], off offset:64
	v_mfma_f32_16x16x32_bf16 v[34:37], v[236:239], v[216:219], 0
	ds_read_b128 v[232:235], v95 offset:17408
	ds_read_b128 v[42:45], v95 offset:42816
	s_waitcnt lgkmcnt(0)
	v_mfma_f32_16x16x32_bf16 v[34:37], v[42:45], v[220:223], v[34:37]
	v_mfma_f32_16x16x32_bf16 v[34:37], v[244:247], v[48:51], v[34:37]
	ds_read_b128 v[216:219], v95 offset:17472
	v_mfma_f32_16x16x32_bf16 v[34:37], v[224:227], v[52:55], v[34:37]
	ds_read_b128 v[236:239], v120 offset:64
	v_mfma_f32_16x16x32_bf16 v[34:37], v[248:251], v[56:59], v[34:37]
	ds_read_b128 v[220:223], v95 offset:19712
	v_mfma_f32_16x16x32_bf16 v[34:37], v[252:255], v[60:63], v[34:37]
	ds_read_b128 v[244:247], v95 offset:19776
	s_nop 7
	v_cvt_pk_bf16_f32 v34, v34, v35
	v_cvt_pk_bf16_f32 v35, v36, v37
	global_store_dwordx2 v[32:33], v[34:35], off offset:96
	ds_read_b128 v[36:39], v46 offset:35840
	ds_read_b128 v[32:35], v46 offset:35904
	v_pk_mul_f32 v[12:13], v[12:13], v[228:229]
	ds_read_b128 v[224:227], v120 offset:128
	v_pk_mul_f32 v[14:15], v[14:15], v[230:231]
	s_waitcnt lgkmcnt(2)
	s_nop 0
	v_mfma_f32_16x16x32_bf16 v[12:15], v[232:235], v[36:39], v[12:15]
	ds_read_b128 v[248:251], v95 offset:22016
	s_waitcnt lgkmcnt(2)
	v_mfma_f32_16x16x32_bf16 v[12:15], v[216:219], v[32:35], v[12:15]
	ds_read_b128 v[252:255], v95 offset:22080
	v_pk_mul_f32 v[0:1], v[0:1], v[236:237]
	ds_read_b128 v[228:231], v120 offset:192
	v_pk_mul_f32 v[2:3], v[2:3], v[238:239]
	s_nop 1
	v_mfma_f32_16x16x32_bf16 v[0:3], v[220:223], v[36:39], v[0:3]
	ds_read_b128 v[232:235], v95 offset:24320
	v_mfma_f32_16x16x32_bf16 v[0:3], v[244:247], v[32:35], v[0:3]
	ds_read_b128 v[216:219], v95 offset:24384
	s_waitcnt lgkmcnt(5)
	v_pk_mul_f32 v[8:9], v[8:9], v[224:225]
	ds_read_b128 v[236:239], v120 offset:256
	v_pk_mul_f32 v[10:11], v[10:11], v[226:227]
	s_waitcnt lgkmcnt(5)
	s_nop 0
	v_mfma_f32_16x16x32_bf16 v[8:11], v[248:251], v[36:39], v[8:11]
	ds_read_b128 v[220:223], v95 offset:26624
	s_waitcnt lgkmcnt(5)
	v_mfma_f32_16x16x32_bf16 v[8:11], v[252:255], v[32:35], v[8:11]
	ds_read_b128 v[244:247], v95 offset:26688
	s_waitcnt lgkmcnt(5)
	v_pk_mul_f32 v[4:5], v[4:5], v[228:229]
	ds_read_b128 v[224:227], v120 offset:320
	v_pk_mul_f32 v[6:7], v[6:7], v[230:231]
	s_waitcnt lgkmcnt(5)
	s_nop 0
	v_mfma_f32_16x16x32_bf16 v[4:7], v[232:235], v[36:39], v[4:7]
	ds_read_b128 v[248:251], v95 offset:28928
	s_waitcnt lgkmcnt(5)
	v_mfma_f32_16x16x32_bf16 v[4:7], v[216:219], v[32:35], v[4:7]
	ds_read_b128 v[252:255], v95 offset:28992
	s_waitcnt lgkmcnt(5)
	v_pk_mul_f32 v[20:21], v[20:21], v[236:237]
	ds_read_b128 v[228:231], v120 offset:384
	v_pk_mul_f32 v[22:23], v[22:23], v[238:239]
	s_waitcnt lgkmcnt(5)
	s_nop 0
	v_mfma_f32_16x16x32_bf16 v[20:23], v[220:223], v[36:39], v[20:23]
	ds_read_b128 v[232:235], v95 offset:31232
	s_waitcnt lgkmcnt(5)
	v_mfma_f32_16x16x32_bf16 v[20:23], v[244:247], v[32:35], v[20:23]
	ds_read_b128 v[216:219], v95 offset:31296
	s_waitcnt lgkmcnt(5)
	v_pk_mul_f32 v[16:17], v[16:17], v[224:225]
	ds_read_b128 v[236:239], v120 offset:448
	v_pk_mul_f32 v[18:19], v[18:19], v[226:227]
	s_waitcnt lgkmcnt(5)
	s_nop 0
	v_mfma_f32_16x16x32_bf16 v[16:19], v[248:251], v[36:39], v[16:19]
	s_waitcnt lgkmcnt(4)
	v_mfma_f32_16x16x32_bf16 v[16:19], v[252:255], v[32:35], v[16:19]
	s_waitcnt lgkmcnt(3)
	v_pk_mul_f32 v[24:25], v[24:25], v[228:229]
	v_pk_mul_f32 v[26:27], v[26:27], v[230:231]
	s_waitcnt lgkmcnt(2)
	s_nop 0
	v_mfma_f32_16x16x32_bf16 v[24:27], v[232:235], v[36:39], v[24:27]
	s_waitcnt lgkmcnt(1)
	v_mfma_f32_16x16x32_bf16 v[24:27], v[216:219], v[32:35], v[24:27]
	s_waitcnt lgkmcnt(0)
	v_pk_mul_f32 v[28:29], v[28:29], v[236:237]
	v_pk_mul_f32 v[30:31], v[30:31], v[238:239]
	ds_read_b128 v[40:43], v95 offset:33536
	s_waitcnt lgkmcnt(0)
	v_mfma_f32_16x16x32_bf16 v[28:31], v[40:43], v[36:39], v[28:31]
	ds_read_b128 v[36:39], v95 offset:33600
	s_waitcnt lgkmcnt(0)
	s_barrier
	v_mfma_f32_16x16x32_bf16 v[28:31], v[36:39], v[32:35], v[28:31]
	s_andn2_b64 exec, exec, s[56:57]
	s_cbranch_execz .LBB0_1511
